# code placement: every hot MFMA loop (GEMM K-loops, attention loops) padded (never-executed s_nop behind s_branch) so that it lies inside one 4 KiB page
# speedup vs baseline: 1.0118x; 1.0037x over previous
; template <class Epi, class Sched, bool ALIGN_EPI = false, bool SP2 = false>
; __device__ __forceinline__ void gemm_phase(PG8_LAS unsigned char* lds, const Gemm g, const Sched S, const Epi E) {
;     ...
;         const bool has_next = S.next(ui + 1, nxt);
;         const char* nA = has_next ? (const char*)g.A + (size_t)nxt.pm * tstep : cA; const char* nB = has_next ? (const char*)g.Bt + (size_t)nxt.pn * tstep : cB;
;     ...
; #pragma unroll
;         for (int a = 0; a < 2; ++a)
; #pragma unroll
;             for (int b = 0; b < 2; ++b)
; #pragma unroll
;                 for (int m = 0; m < 4; ++m)
; #pragma unroll
;                     for (int n = 0; n < 2; ++n) acc[a][b][m][n] = (f32x4){0.f, 0.f, 0.f, 0.f};
;         cur = nxt; cA = nA; cB = nB; ++ui;
.LBB0_275:
	s_ashr_i32 s19, s18, 31
	s_lshl_b64 s[24:25], s[18:19], 19
	s_add_u32 s24, s56, s24
	s_addc_u32 s25, s57, s25
	s_and_b64 s[38:39], s[0:1], exec
	s_cselect_b32 s19, s25, s43
	s_cselect_b32 s63, s24, s42
	s_ashr_i32 s17, s16, 31
	s_lshl_b64 s[38:39], s[16:17], 19
	s_add_u32 s38, s4, s38
	s_addc_u32 s39, s5, s39
	s_and_b64 s[50:51], s[0:1], exec
	s_cselect_b32 s17, s39, s45
	s_cselect_b32 s64, s38, s44
	s_add_u32 s42, s42, 0x40080
	s_addc_u32 s43, s43, 0
	s_add_u32 s65, s44, 0x100
	v_mov_b32_e32 v0, 0
	s_addc_u32 s68, s45, 0
	s_mov_b32 s69, -2
	v_mov_b32_e32 v1, v0
	v_mov_b32_e32 v2, v0
	v_mov_b32_e32 v3, v0
	v_mov_b32_e32 v8, v0
	v_mov_b32_e32 v9, v0
	v_mov_b32_e32 v10, v0
	v_mov_b32_e32 v11, v0
	v_mov_b32_e32 v16, v0
	v_mov_b32_e32 v17, v0
	v_mov_b32_e32 v18, v0
	v_mov_b32_e32 v19, v0
	v_mov_b32_e32 v24, v0
	v_mov_b32_e32 v25, v0
	v_mov_b32_e32 v26, v0
	v_mov_b32_e32 v27, v0
	v_mov_b32_e32 v32, v0
	v_mov_b32_e32 v33, v0
	v_mov_b32_e32 v34, v0
	v_mov_b32_e32 v35, v0
	v_mov_b32_e32 v40, v0
	v_mov_b32_e32 v41, v0
	v_mov_b32_e32 v42, v0
	v_mov_b32_e32 v43, v0
	v_mov_b32_e32 v48, v0
	v_mov_b32_e32 v49, v0
	v_mov_b32_e32 v50, v0
	v_mov_b32_e32 v51, v0
	v_mov_b32_e32 v56, v0
	v_mov_b32_e32 v57, v0
	v_mov_b32_e32 v58, v0
	v_mov_b32_e32 v59, v0
	v_mov_b32_e32 v4, v0
	v_mov_b32_e32 v5, v0
	v_mov_b32_e32 v6, v0
	v_mov_b32_e32 v7, v0
	v_mov_b32_e32 v12, v0
	v_mov_b32_e32 v13, v0
	v_mov_b32_e32 v14, v0
	v_mov_b32_e32 v15, v0
	v_mov_b32_e32 v20, v0
	v_mov_b32_e32 v21, v0
	v_mov_b32_e32 v22, v0
	v_mov_b32_e32 v23, v0
	v_mov_b32_e32 v28, v0
	v_mov_b32_e32 v29, v0
	v_mov_b32_e32 v30, v0
	v_mov_b32_e32 v31, v0
	v_mov_b32_e32 v36, v0
	v_mov_b32_e32 v37, v0
	v_mov_b32_e32 v38, v0
	v_mov_b32_e32 v39, v0
	v_mov_b32_e32 v44, v0
	v_mov_b32_e32 v45, v0
	v_mov_b32_e32 v46, v0
	v_mov_b32_e32 v47, v0
	v_mov_b32_e32 v52, v0
	v_mov_b32_e32 v53, v0
	v_mov_b32_e32 v54, v0
	v_mov_b32_e32 v55, v0
	v_mov_b32_e32 v60, v0
	v_mov_b32_e32 v61, v0
	v_mov_b32_e32 v62, v0
	v_mov_b32_e32 v63, v0
	v_mov_b32_e32 v64, v0
	v_mov_b32_e32 v65, v0
	v_mov_b32_e32 v66, v0
	v_mov_b32_e32 v67, v0
	v_mov_b32_e32 v72, v0
	v_mov_b32_e32 v73, v0
	v_mov_b32_e32 v74, v0
	v_mov_b32_e32 v75, v0
	v_mov_b32_e32 v80, v0
	v_mov_b32_e32 v81, v0
	v_mov_b32_e32 v82, v0
	v_mov_b32_e32 v83, v0
	v_mov_b32_e32 v88, v0
	v_mov_b32_e32 v89, v0
	v_mov_b32_e32 v90, v0
	v_mov_b32_e32 v91, v0
	v_mov_b32_e32 v96, v0
	v_mov_b32_e32 v97, v0
	v_mov_b32_e32 v98, v0
	v_mov_b32_e32 v99, v0
	v_mov_b32_e32 v104, v0
	v_mov_b32_e32 v105, v0
	v_mov_b32_e32 v106, v0
	v_mov_b32_e32 v107, v0
	v_mov_b32_e32 v112, v0
	v_mov_b32_e32 v113, v0
	v_mov_b32_e32 v114, v0
	v_mov_b32_e32 v115, v0
	v_mov_b32_e32 v120, v0
	v_mov_b32_e32 v121, v0
	v_mov_b32_e32 v122, v0
	v_mov_b32_e32 v123, v0
	v_mov_b32_e32 v68, v0
	v_mov_b32_e32 v69, v0
	v_mov_b32_e32 v70, v0
	v_mov_b32_e32 v71, v0
	v_mov_b32_e32 v76, v0
	v_mov_b32_e32 v77, v0
	v_mov_b32_e32 v78, v0
	v_mov_b32_e32 v79, v0
	v_mov_b32_e32 v84, v0
	v_mov_b32_e32 v85, v0
	v_mov_b32_e32 v86, v0
	v_mov_b32_e32 v87, v0
	v_mov_b32_e32 v92, v0
	v_mov_b32_e32 v93, v0
	v_mov_b32_e32 v94, v0
	v_mov_b32_e32 v95, v0
	v_mov_b32_e32 v100, v0
	v_mov_b32_e32 v101, v0
	v_mov_b32_e32 v102, v0
	v_mov_b32_e32 v103, v0
	v_mov_b32_e32 v108, v0
	v_mov_b32_e32 v109, v0
	v_mov_b32_e32 v110, v0
	v_mov_b32_e32 v111, v0
	v_mov_b32_e32 v116, v0
	v_mov_b32_e32 v117, v0
	v_mov_b32_e32 v118, v0
	v_mov_b32_e32 v119, v0
	v_mov_b32_e32 v124, v0
	v_mov_b32_e32 v125, v0
	v_mov_b32_e32 v126, v0
	v_mov_b32_e32 v127, v0
	s_branch .Lpagefit_1
	s_nop 0
	s_nop 0
	s_nop 0
	s_nop 0
	s_nop 0
	s_nop 0
	s_nop 0
	s_nop 0
	s_nop 0
	s_nop 0
	s_nop 0
	s_nop 0
	s_nop 0
	s_nop 0
	s_nop 0
	s_nop 0
	s_nop 0
	s_nop 0
	s_nop 0
	s_nop 0
	s_nop 0
	s_nop 0
	s_nop 0
	s_nop 0
	s_nop 0
	s_nop 0
	s_nop 0
	s_nop 0
	s_nop 0
	s_nop 0
	s_nop 0
	s_nop 0
	s_nop 0
	s_nop 0
	s_nop 0
	s_nop 0
	s_nop 0
	s_nop 0
	s_nop 0
	s_nop 0
	s_nop 0
	s_nop 0
	s_nop 0
	s_nop 0
	s_nop 0
	s_nop 0
	s_nop 0
	s_nop 0
	s_nop 0
	s_nop 0
	s_nop 0
	s_nop 0
	s_nop 0
	s_nop 0
	s_nop 0
	s_nop 0
	s_nop 0
	s_nop 0
	s_nop 0
	s_nop 0
	s_nop 0
	s_nop 0
	s_nop 0
	s_nop 0
	s_nop 0
	s_nop 0
	s_nop 0
	s_nop 0
	s_nop 0
	s_nop 0
	s_nop 0
	s_nop 0
	s_nop 0
	s_nop 0
	s_nop 0
	s_nop 0
	s_nop 0
	s_nop 0
	s_nop 0
	s_nop 0
	s_nop 0
	s_nop 0
	s_nop 0
	s_nop 0
	s_nop 0
	s_nop 0
	s_nop 0
	s_nop 0
	s_nop 0
	s_nop 0
	s_nop 0
	s_nop 0
	s_nop 0
; #define PG8_STAGE(bufoff, gbase, voff) do { _Pragma("unroll") for (int _i = 0; _i < 2; ++_i) \
;         __builtin_amdgcn_global_load_lds((const unsigned*)((const char*)(gbase) + (voff)[_i]), (PG8_LAS unsigned*)(lds + (bufoff) + ldsw + _i * 8192), 16, 0, 0); } while (0)
; #define PG8_LDA(dst, b, h) do { _Pragma("unroll") for (int m = 0; m < 4; ++m) _Pragma("unroll") for (int k = 0; k < 2; ++k) dst[m][k] = *(const PG8_LAS bf16x8*)(lds + PG8_SA(b, h) + aoff + m * 2048 + k * 1024); } while (0)
; #define PG8_LDB(dst, b, h) do { _Pragma("unroll") for (int n = 0; n < 2; ++n) _Pragma("unroll") for (int k = 0; k < 2; ++k) dst[n][k] = *(const PG8_LAS bf16x8*)(lds + PG8_SB(b, h) + boff + n * 2048 + k * 1024); } while (0)
; #define PG8_MMA(ai, bj, At, Bt) do { __builtin_amdgcn_s_setprio(1); _Pragma("unroll") for (int m = 0; m < 4; ++m) _Pragma("unroll") for (int n = 0; n < 2; ++n) _Pragma("unroll") for (int k = 0; k < 2; ++k) \
;         acc[ai][bj][m][n] = __builtin_amdgcn_mfma_f32_16x16x32_bf16(Bt[n][k], At[m][k], acc[ai][bj][m][n], 0, 0, 0); __builtin_amdgcn_s_setprio(0); } while (0)
; #define PG8_WAIT_V(n) asm volatile("s_waitcnt vmcnt(" #n ")" ::: "memory")
; #define PG8_WAIT_L(n) asm volatile("s_waitcnt lgkmcnt(" #n ")" ::: "memory")
; #define PG8_BAR __builtin_amdgcn_s_barrier()
; #define PG8_SCHED __builtin_amdgcn_sched_barrier(0)
; template <class Epi, class Sched, bool ALIGN_EPI = false, bool SP2 = false>
; __device__ __forceinline__ void gemm_phase(PG8_LAS unsigned char* lds, const Gemm g, const Sched S, const Epi E) {
;     ...
;         for (int t = 0; t < nt; t += 2) {
;             if constexpr (Epi::MIDT >= 0) { if (t == Epi::MIDT) E.mid(acc, cur, wr, fr); }
;             const bool last = (t == nt - 2);
;             const char* a1 = cA + (size_t)(t + 1) * kstep;
;             const char* a2 = last ? nA : cA + (size_t)(t + 2) * kstep; const char* b2 = last ? nB : cB + (size_t)(t + 2) * kstep;
;             const char* a3 = a2 + kstep; const char* b3 = b2 + kstep;
;             if (last && has_next) S.a_ready(nxt);
;             if constexpr (SP2) {
;             PG8_LDB(B0, 0, 0); PG8_LDB(B1, 0, 1); PG8_SCHED; PG8_LDA(At, 0, 0); PG8_STAGE(PG8_SA(1, 1), a1 + hstep, voffA);
;             PG8_WAIT_V(8); PG8_WAIT_L(0); PG8_BAR; PG8_MMA(0, 0, At, B0); PG8_MMA(0, 1, At, B1); PG8_BAR; PG8_SCHED;
.Lpagefit_1:
.LBB0_276:
	ds_read_b128 v[152:155], v149
	ds_read_b128 v[156:159], v149 offset:1024
	ds_read_b128 v[160:163], v149 offset:2048
	ds_read_b128 v[164:167], v149 offset:3072
	ds_read_b128 v[168:171], v150
	ds_read_b128 v[172:175], v150 offset:1024
	ds_read_b128 v[176:179], v150 offset:2048
	ds_read_b128 v[180:183], v150 offset:3072
	s_add_u32 s44, s42, 0xfffc0080
	s_addc_u32 s45, s43, -1
	s_cmp_eq_u32 s69, 12
	s_cselect_b32 s51, s19, s45
	s_cselect_b32 s50, s63, s44
	s_cselect_b32 s45, s17, s68
	s_cselect_b32 s44, s64, s65
	v_lshl_add_u64 v[144:145], s[42:43], 0, v[136:137]
	s_add_i32 m0, s33, 0xc000
	ds_read_b128 v[190:193], v151
	ds_read_b128 v[194:197], v151 offset:1024
	ds_read_b128 v[198:201], v151 offset:2048
	ds_read_b128 v[202:205], v151 offset:3072
	ds_read_b128 v[206:209], v151 offset:4096
	ds_read_b128 v[210:213], v151 offset:5120
	ds_read_b128 v[214:217], v151 offset:6144
	ds_read_b128 v[218:221], v151 offset:7168
	global_load_lds_dwordx4 v[144:145], off
	v_lshl_add_u64 v[144:145], s[42:43], 0, v[138:139]
	s_add_i32 m0, s33, 0xe000
	s_nop 0
	global_load_lds_dwordx4 v[144:145], off
	s_waitcnt vmcnt(8)
	s_waitcnt lgkmcnt(0)
	s_barrier
	s_setprio 1
	s_waitcnt lgkmcnt(0)
	v_mfma_f32_16x16x32_bf16 v[124:127], v[152:155], v[190:193], v[124:127]
	v_mfma_f32_16x16x32_bf16 v[116:119], v[160:163], v[190:193], v[116:119]
	v_mfma_f32_16x16x32_bf16 v[108:111], v[152:155], v[198:201], v[108:111]
	v_mfma_f32_16x16x32_bf16 v[100:103], v[160:163], v[198:201], v[100:103]
	v_mfma_f32_16x16x32_bf16 v[92:95], v[152:155], v[206:209], v[92:95]
	v_mfma_f32_16x16x32_bf16 v[84:87], v[160:163], v[206:209], v[84:87]
	v_mfma_f32_16x16x32_bf16 v[76:79], v[152:155], v[214:217], v[76:79]
	v_mfma_f32_16x16x32_bf16 v[68:71], v[160:163], v[214:217], v[68:71]
	v_mfma_f32_16x16x32_bf16 v[124:127], v[156:159], v[194:197], v[124:127]
	v_mfma_f32_16x16x32_bf16 v[116:119], v[164:167], v[194:197], v[116:119]
	v_mfma_f32_16x16x32_bf16 v[108:111], v[156:159], v[202:205], v[108:111]
	v_mfma_f32_16x16x32_bf16 v[100:103], v[164:167], v[202:205], v[100:103]
	v_mfma_f32_16x16x32_bf16 v[92:95], v[156:159], v[210:213], v[92:95]
	v_mfma_f32_16x16x32_bf16 v[84:87], v[164:167], v[210:213], v[84:87]
	v_mfma_f32_16x16x32_bf16 v[76:79], v[156:159], v[218:221], v[76:79]
	v_mfma_f32_16x16x32_bf16 v[68:71], v[164:167], v[218:221], v[68:71]
	s_setprio 0
	s_setprio 1
	v_mfma_f32_16x16x32_bf16 v[120:123], v[168:171], v[190:193], v[120:123]
	v_mfma_f32_16x16x32_bf16 v[112:115], v[176:179], v[190:193], v[112:115]
	v_mfma_f32_16x16x32_bf16 v[104:107], v[168:171], v[198:201], v[104:107]
	v_mfma_f32_16x16x32_bf16 v[96:99], v[176:179], v[198:201], v[96:99]
	v_mfma_f32_16x16x32_bf16 v[88:91], v[168:171], v[206:209], v[88:91]
	v_mfma_f32_16x16x32_bf16 v[80:83], v[176:179], v[206:209], v[80:83]
	v_mfma_f32_16x16x32_bf16 v[72:75], v[168:171], v[214:217], v[72:75]
	v_mfma_f32_16x16x32_bf16 v[64:67], v[176:179], v[214:217], v[64:67]
	v_mfma_f32_16x16x32_bf16 v[120:123], v[172:175], v[194:197], v[120:123]
	v_mfma_f32_16x16x32_bf16 v[112:115], v[180:183], v[194:197], v[112:115]
	v_mfma_f32_16x16x32_bf16 v[104:107], v[172:175], v[202:205], v[104:107]
	v_mfma_f32_16x16x32_bf16 v[96:99], v[180:183], v[202:205], v[96:99]
	v_mfma_f32_16x16x32_bf16 v[88:91], v[172:175], v[210:213], v[88:91]
	v_mfma_f32_16x16x32_bf16 v[80:83], v[180:183], v[210:213], v[80:83]
	v_mfma_f32_16x16x32_bf16 v[72:75], v[172:175], v[218:221], v[72:75]
	v_mfma_f32_16x16x32_bf16 v[64:67], v[180:183], v[218:221], v[64:67]
	s_setprio 0
	s_barrier
	s_add_i32 s82, s59, s8
	v_lshl_add_u64 v[144:145], s[44:45], 0, v[132:133]
	s_mov_b32 m0, s82
	ds_read_b128 v[190:193], v151 offset:16384
	ds_read_b128 v[194:197], v151 offset:17408
	ds_read_b128 v[198:201], v151 offset:18432
	ds_read_b128 v[202:205], v151 offset:19456
	ds_read_b128 v[206:209], v151 offset:20480
	ds_read_b128 v[210:213], v151 offset:21504
	ds_read_b128 v[214:217], v151 offset:22528
	ds_read_b128 v[218:221], v151 offset:23552
	global_load_lds_dwordx4 v[144:145], off
	s_add_i32 m0, s82, 0x2000
	s_add_u32 s82, s44, 0x40000
	v_lshl_add_u64 v[184:185], s[44:45], 0, v[128:129]
	s_addc_u32 s83, s45, 0
	s_add_i32 s84, s60, s8
	global_load_lds_dwordx4 v[184:185], off
	v_lshl_add_u64 v[222:223], s[82:83], 0, v[132:133]
	s_mov_b32 m0, s84
	v_lshl_add_u64 v[224:225], s[50:51], 0, v[130:131]
	global_load_lds_dwordx4 v[222:223], off
	v_lshl_add_u64 v[222:223], s[82:83], 0, v[128:129]
	s_add_i32 m0, s84, 0x2000
	s_nop 0
	global_load_lds_dwordx4 v[222:223], off
	v_lshl_add_u64 v[222:223], s[50:51], 0, v[134:135]
	s_mov_b32 m0, s33
	s_nop 0
	global_load_lds_dwordx4 v[222:223], off
	s_mov_b32 m0, s36
	s_nop 0
	global_load_lds_dwordx4 v[224:225], off
	s_waitcnt vmcnt(8)
	s_waitcnt lgkmcnt(0)
	s_barrier
; #define PG8_STAGE(bufoff, gbase, voff) do { _Pragma("unroll") for (int _i = 0; _i < 2; ++_i) \
;         __builtin_amdgcn_global_load_lds((const unsigned*)((const char*)(gbase) + (voff)[_i]), (PG8_LAS unsigned*)(lds + (bufoff) + ldsw + _i * 8192), 16, 0, 0); } while (0)
; #define PG8_LDA(dst, b, h) do { _Pragma("unroll") for (int m = 0; m < 4; ++m) _Pragma("unroll") for (int k = 0; k < 2; ++k) dst[m][k] = *(const PG8_LAS bf16x8*)(lds + PG8_SA(b, h) + aoff + m * 2048 + k * 1024); } while (0)
; #define PG8_LDB(dst, b, h) do { _Pragma("unroll") for (int n = 0; n < 2; ++n) _Pragma("unroll") for (int k = 0; k < 2; ++k) dst[n][k] = *(const PG8_LAS bf16x8*)(lds + PG8_SB(b, h) + boff + n * 2048 + k * 1024); } while (0)
; #define PG8_MMA(ai, bj, At, Bt) do { __builtin_amdgcn_s_setprio(1); _Pragma("unroll") for (int m = 0; m < 4; ++m) _Pragma("unroll") for (int n = 0; n < 2; ++n) _Pragma("unroll") for (int k = 0; k < 2; ++k) \
;         acc[ai][bj][m][n] = __builtin_amdgcn_mfma_f32_16x16x32_bf16(Bt[n][k], At[m][k], acc[ai][bj][m][n], 0, 0, 0); __builtin_amdgcn_s_setprio(0); } while (0)
; #define PG8_WAIT_V(n) asm volatile("s_waitcnt vmcnt(" #n ")" ::: "memory")
; #define PG8_WAIT_L(n) asm volatile("s_waitcnt lgkmcnt(" #n ")" ::: "memory")
; #define PG8_BAR __builtin_amdgcn_s_barrier()
; #define PG8_SCHED __builtin_amdgcn_sched_barrier(0)
; template <class Epi, class Sched, bool ALIGN_EPI = false, bool SP2 = false>
; __device__ __forceinline__ void gemm_phase(PG8_LAS unsigned char* lds, const Gemm g, const Sched S, const Epi E) {
;     ...
;             PG8_WAIT_V(8); PG8_WAIT_L(0); PG8_BAR; PG8_MMA(0, 0, At, B0); PG8_MMA(0, 1, At, B1); PG8_BAR; PG8_SCHED;
;             PG8_LDA(At, 0, 1); PG8_STAGE(PG8_SB(0, 0), b2, voffB); PG8_STAGE(PG8_SB(0, 1), b2 + hstep, voffB); PG8_STAGE(PG8_SA(0, 0), a2, voffA);
;             PG8_WAIT_V(8); PG8_WAIT_L(0); PG8_BAR; PG8_MMA(1, 0, At, B0); PG8_MMA(1, 1, At, B1); PG8_BAR; PG8_SCHED;
;             PG8_LDB(B0, 1, 0); PG8_LDB(B1, 1, 1); PG8_SCHED; PG8_LDA(At, 1, 0); PG8_STAGE(PG8_SA(0, 1), a2 + hstep, voffA);
;             PG8_WAIT_V(8); PG8_WAIT_L(0); PG8_BAR; PG8_MMA(0, 0, At, B0); PG8_MMA(0, 1, At, B1); PG8_BAR; PG8_SCHED;
	s_setprio 1
	s_waitcnt lgkmcnt(0)
	v_mfma_f32_16x16x32_bf16 v[60:63], v[152:155], v[190:193], v[60:63]
	v_mfma_f32_16x16x32_bf16 v[52:55], v[160:163], v[190:193], v[52:55]
	v_mfma_f32_16x16x32_bf16 v[44:47], v[152:155], v[198:201], v[44:47]
	v_mfma_f32_16x16x32_bf16 v[36:39], v[160:163], v[198:201], v[36:39]
	v_mfma_f32_16x16x32_bf16 v[28:31], v[152:155], v[206:209], v[28:31]
	v_mfma_f32_16x16x32_bf16 v[20:23], v[160:163], v[206:209], v[20:23]
	v_mfma_f32_16x16x32_bf16 v[12:15], v[152:155], v[214:217], v[12:15]
	v_mfma_f32_16x16x32_bf16 v[4:7], v[160:163], v[214:217], v[4:7]
	v_mfma_f32_16x16x32_bf16 v[60:63], v[156:159], v[194:197], v[60:63]
	v_mfma_f32_16x16x32_bf16 v[52:55], v[164:167], v[194:197], v[52:55]
	v_mfma_f32_16x16x32_bf16 v[44:47], v[156:159], v[202:205], v[44:47]
	v_mfma_f32_16x16x32_bf16 v[36:39], v[164:167], v[202:205], v[36:39]
	v_mfma_f32_16x16x32_bf16 v[28:31], v[156:159], v[210:213], v[28:31]
	v_mfma_f32_16x16x32_bf16 v[20:23], v[164:167], v[210:213], v[20:23]
	v_mfma_f32_16x16x32_bf16 v[12:15], v[156:159], v[218:221], v[12:15]
	v_mfma_f32_16x16x32_bf16 v[4:7], v[164:167], v[218:221], v[4:7]
	s_setprio 0
	s_setprio 1
	v_mfma_f32_16x16x32_bf16 v[56:59], v[168:171], v[190:193], v[56:59]
	v_mfma_f32_16x16x32_bf16 v[48:51], v[176:179], v[190:193], v[48:51]
	v_mfma_f32_16x16x32_bf16 v[40:43], v[168:171], v[198:201], v[40:43]
	v_mfma_f32_16x16x32_bf16 v[32:35], v[176:179], v[198:201], v[32:35]
	v_mfma_f32_16x16x32_bf16 v[24:27], v[168:171], v[206:209], v[24:27]
	v_mfma_f32_16x16x32_bf16 v[16:19], v[176:179], v[206:209], v[16:19]
	v_mfma_f32_16x16x32_bf16 v[8:11], v[168:171], v[214:217], v[8:11]
	v_mfma_f32_16x16x32_bf16 v[0:3], v[176:179], v[214:217], v[0:3]
	v_mfma_f32_16x16x32_bf16 v[56:59], v[172:175], v[194:197], v[56:59]
	v_mfma_f32_16x16x32_bf16 v[48:51], v[180:183], v[194:197], v[48:51]
	v_mfma_f32_16x16x32_bf16 v[40:43], v[172:175], v[202:205], v[40:43]
	v_mfma_f32_16x16x32_bf16 v[32:35], v[180:183], v[202:205], v[32:35]
	v_mfma_f32_16x16x32_bf16 v[24:27], v[172:175], v[210:213], v[24:27]
	v_mfma_f32_16x16x32_bf16 v[16:19], v[180:183], v[210:213], v[16:19]
	v_mfma_f32_16x16x32_bf16 v[8:11], v[172:175], v[218:221], v[8:11]
	v_mfma_f32_16x16x32_bf16 v[0:3], v[180:183], v[218:221], v[0:3]
	s_setprio 0
	s_barrier
	s_add_i32 s82, 0, 0x18000
	s_add_i32 s83, 0, 0x1c000
	v_add_u32_e32 v164, s82, v148
	v_add_u32_e32 v180, s83, v148
	ds_read_b128 v[152:155], v164
	ds_read_b128 v[156:159], v164 offset:1024
	ds_read_b128 v[160:163], v164 offset:2048
	ds_read_b128 v[164:167], v164 offset:3072
	ds_read_b128 v[168:171], v180
	ds_read_b128 v[172:175], v180 offset:1024
	ds_read_b128 v[176:179], v180 offset:2048
	ds_read_b128 v[180:183], v180 offset:3072
	s_add_u32 s50, s50, 0x40000
	s_addc_u32 s51, s51, 0
	s_mov_b32 m0, s37
	v_lshl_add_u64 v[226:227], s[50:51], 0, v[134:135]
	ds_read_b128 v[190:193], v151 offset:32768
	ds_read_b128 v[194:197], v151 offset:33792
	ds_read_b128 v[198:201], v151 offset:34816
	ds_read_b128 v[202:205], v151 offset:35840
	ds_read_b128 v[206:209], v151 offset:36864
	ds_read_b128 v[210:213], v151 offset:37888
	ds_read_b128 v[214:217], v151 offset:38912
	ds_read_b128 v[218:221], v151 offset:39936
	global_load_lds_dwordx4 v[226:227], off
	v_lshl_add_u64 v[226:227], s[50:51], 0, v[130:131]
	s_mov_b32 m0, s41
	s_nop 0
	global_load_lds_dwordx4 v[226:227], off
	s_waitcnt vmcnt(8)
	s_waitcnt lgkmcnt(0)
	s_barrier
	s_setprio 1
	s_waitcnt lgkmcnt(0)
	v_mfma_f32_16x16x32_bf16 v[124:127], v[152:155], v[190:193], v[124:127]
	v_mfma_f32_16x16x32_bf16 v[116:119], v[160:163], v[190:193], v[116:119]
	v_mfma_f32_16x16x32_bf16 v[108:111], v[152:155], v[198:201], v[108:111]
	v_mfma_f32_16x16x32_bf16 v[100:103], v[160:163], v[198:201], v[100:103]
	v_mfma_f32_16x16x32_bf16 v[92:95], v[152:155], v[206:209], v[92:95]
	v_mfma_f32_16x16x32_bf16 v[84:87], v[160:163], v[206:209], v[84:87]
	v_mfma_f32_16x16x32_bf16 v[76:79], v[152:155], v[214:217], v[76:79]
	v_mfma_f32_16x16x32_bf16 v[68:71], v[160:163], v[214:217], v[68:71]
	v_mfma_f32_16x16x32_bf16 v[124:127], v[156:159], v[194:197], v[124:127]
	v_mfma_f32_16x16x32_bf16 v[116:119], v[164:167], v[194:197], v[116:119]
	v_mfma_f32_16x16x32_bf16 v[108:111], v[156:159], v[202:205], v[108:111]
	v_mfma_f32_16x16x32_bf16 v[100:103], v[164:167], v[202:205], v[100:103]
	v_mfma_f32_16x16x32_bf16 v[92:95], v[156:159], v[210:213], v[92:95]
	v_mfma_f32_16x16x32_bf16 v[84:87], v[164:167], v[210:213], v[84:87]
	v_mfma_f32_16x16x32_bf16 v[76:79], v[156:159], v[218:221], v[76:79]
	v_mfma_f32_16x16x32_bf16 v[68:71], v[164:167], v[218:221], v[68:71]
	s_setprio 0
	s_setprio 1
	v_mfma_f32_16x16x32_bf16 v[120:123], v[168:171], v[190:193], v[120:123]
	v_mfma_f32_16x16x32_bf16 v[112:115], v[176:179], v[190:193], v[112:115]
	v_mfma_f32_16x16x32_bf16 v[104:107], v[168:171], v[198:201], v[104:107]
	v_mfma_f32_16x16x32_bf16 v[96:99], v[176:179], v[198:201], v[96:99]
	v_mfma_f32_16x16x32_bf16 v[88:91], v[168:171], v[206:209], v[88:91]
	v_mfma_f32_16x16x32_bf16 v[80:83], v[176:179], v[206:209], v[80:83]
	v_mfma_f32_16x16x32_bf16 v[72:75], v[168:171], v[214:217], v[72:75]
	v_mfma_f32_16x16x32_bf16 v[64:67], v[176:179], v[214:217], v[64:67]
	v_mfma_f32_16x16x32_bf16 v[120:123], v[172:175], v[194:197], v[120:123]
	v_mfma_f32_16x16x32_bf16 v[112:115], v[180:183], v[194:197], v[112:115]
	v_mfma_f32_16x16x32_bf16 v[104:107], v[172:175], v[202:205], v[104:107]
	v_mfma_f32_16x16x32_bf16 v[96:99], v[180:183], v[202:205], v[96:99]
	v_mfma_f32_16x16x32_bf16 v[88:91], v[172:175], v[210:213], v[88:91]
	v_mfma_f32_16x16x32_bf16 v[80:83], v[180:183], v[210:213], v[80:83]
	v_mfma_f32_16x16x32_bf16 v[72:75], v[172:175], v[218:221], v[72:75]
	v_mfma_f32_16x16x32_bf16 v[64:67], v[180:183], v[218:221], v[64:67]
	s_setprio 0
	s_barrier
; #define PG8_STAGE(bufoff, gbase, voff) do { _Pragma("unroll") for (int _i = 0; _i < 2; ++_i) \
;         __builtin_amdgcn_global_load_lds((const unsigned*)((const char*)(gbase) + (voff)[_i]), (PG8_LAS unsigned*)(lds + (bufoff) + ldsw + _i * 8192), 16, 0, 0); } while (0)
; #define PG8_LDA(dst, b, h) do { _Pragma("unroll") for (int m = 0; m < 4; ++m) _Pragma("unroll") for (int k = 0; k < 2; ++k) dst[m][k] = *(const PG8_LAS bf16x8*)(lds + PG8_SA(b, h) + aoff + m * 2048 + k * 1024); } while (0)
; #define PG8_MMA(ai, bj, At, Bt) do { __builtin_amdgcn_s_setprio(1); _Pragma("unroll") for (int m = 0; m < 4; ++m) _Pragma("unroll") for (int n = 0; n < 2; ++n) _Pragma("unroll") for (int k = 0; k < 2; ++k) \
;         acc[ai][bj][m][n] = __builtin_amdgcn_mfma_f32_16x16x32_bf16(Bt[n][k], At[m][k], acc[ai][bj][m][n], 0, 0, 0); __builtin_amdgcn_s_setprio(0); } while (0)
; #define PG8_WAIT_V(n) asm volatile("s_waitcnt vmcnt(" #n ")" ::: "memory")
; #define PG8_WAIT_L(n) asm volatile("s_waitcnt lgkmcnt(" #n ")" ::: "memory")
; #define PG8_BAR __builtin_amdgcn_s_barrier()
; #define PG8_SCHED __builtin_amdgcn_sched_barrier(0)
; template <class Epi, class Sched, bool ALIGN_EPI = false, bool SP2 = false>
; __device__ __forceinline__ void gemm_phase(PG8_LAS unsigned char* lds, const Gemm g, const Sched S, const Epi E) {
;     ...
;             PG8_LDA(At, 1, 1); PG8_STAGE(PG8_SB(1, 0), b3, voffB); PG8_STAGE(PG8_SB(1, 1), b3 + hstep, voffB); PG8_STAGE(PG8_SA(1, 0), a3, voffA);
;             PG8_WAIT_V(8); PG8_WAIT_L(0); PG8_BAR; PG8_MMA(1, 0, At, B0); PG8_MMA(1, 1, At, B1); PG8_BAR; PG8_SCHED;
	s_add_i32 s50, s82, s8
	v_lshl_add_u64 v[144:145], v[144:145], 0, s[12:13]
	s_mov_b32 m0, s50
	ds_read_b128 v[190:193], v151 offset:49152
	ds_read_b128 v[194:197], v151 offset:50176
	ds_read_b128 v[198:201], v151 offset:51200
	ds_read_b128 v[202:205], v151 offset:52224
	ds_read_b128 v[206:209], v151 offset:53248
	ds_read_b128 v[210:213], v151 offset:54272
	ds_read_b128 v[214:217], v151 offset:55296
	ds_read_b128 v[218:221], v151 offset:56320
	global_load_lds_dwordx4 v[144:145], off
	s_add_i32 m0, s50, 0x2000
	s_add_u32 s44, s44, 0x40080
	v_lshl_add_u64 v[144:145], v[184:185], 0, s[12:13]
	s_addc_u32 s45, s45, 0
	s_add_i32 s50, s83, s8
	global_load_lds_dwordx4 v[144:145], off
	v_lshl_add_u64 v[144:145], s[44:45], 0, v[132:133]
	s_mov_b32 m0, s50
	s_nop 0
	global_load_lds_dwordx4 v[144:145], off
	v_lshl_add_u64 v[144:145], s[44:45], 0, v[128:129]
	s_add_i32 m0, s50, 0x2000
	s_nop 0
	global_load_lds_dwordx4 v[144:145], off
	v_lshl_add_u64 v[144:145], v[222:223], 0, s[12:13]
	s_mov_b32 m0, s49
	s_nop 0
	global_load_lds_dwordx4 v[144:145], off
	v_lshl_add_u64 v[144:145], v[224:225], 0, s[12:13]
	s_mov_b32 m0, s54
	s_nop 0
	global_load_lds_dwordx4 v[144:145], off
	s_waitcnt vmcnt(8)
	s_waitcnt lgkmcnt(0)
	s_barrier
	s_setprio 1
	s_waitcnt lgkmcnt(0)
	v_mfma_f32_16x16x32_bf16 v[60:63], v[152:155], v[190:193], v[60:63]
	v_mfma_f32_16x16x32_bf16 v[52:55], v[160:163], v[190:193], v[52:55]
	v_mfma_f32_16x16x32_bf16 v[44:47], v[152:155], v[198:201], v[44:47]
	v_mfma_f32_16x16x32_bf16 v[36:39], v[160:163], v[198:201], v[36:39]
	v_mfma_f32_16x16x32_bf16 v[28:31], v[152:155], v[206:209], v[28:31]
	v_mfma_f32_16x16x32_bf16 v[20:23], v[160:163], v[206:209], v[20:23]
	v_mfma_f32_16x16x32_bf16 v[12:15], v[152:155], v[214:217], v[12:15]
	v_mfma_f32_16x16x32_bf16 v[4:7], v[160:163], v[214:217], v[4:7]
	v_mfma_f32_16x16x32_bf16 v[60:63], v[156:159], v[194:197], v[60:63]
	v_mfma_f32_16x16x32_bf16 v[52:55], v[164:167], v[194:197], v[52:55]
	v_mfma_f32_16x16x32_bf16 v[44:47], v[156:159], v[202:205], v[44:47]
	v_mfma_f32_16x16x32_bf16 v[36:39], v[164:167], v[202:205], v[36:39]
	v_mfma_f32_16x16x32_bf16 v[28:31], v[156:159], v[210:213], v[28:31]
	v_mfma_f32_16x16x32_bf16 v[20:23], v[164:167], v[210:213], v[20:23]
	v_mfma_f32_16x16x32_bf16 v[12:15], v[156:159], v[218:221], v[12:15]
	v_mfma_f32_16x16x32_bf16 v[4:7], v[164:167], v[218:221], v[4:7]
	s_setprio 0
	s_setprio 1
	v_mfma_f32_16x16x32_bf16 v[56:59], v[168:171], v[190:193], v[56:59]
	v_mfma_f32_16x16x32_bf16 v[48:51], v[176:179], v[190:193], v[48:51]
	v_mfma_f32_16x16x32_bf16 v[40:43], v[168:171], v[198:201], v[40:43]
	v_mfma_f32_16x16x32_bf16 v[32:35], v[176:179], v[198:201], v[32:35]
	v_mfma_f32_16x16x32_bf16 v[24:27], v[168:171], v[206:209], v[24:27]
	v_mfma_f32_16x16x32_bf16 v[16:19], v[176:179], v[206:209], v[16:19]
	v_mfma_f32_16x16x32_bf16 v[8:11], v[168:171], v[214:217], v[8:11]
	v_mfma_f32_16x16x32_bf16 v[0:3], v[176:179], v[214:217], v[0:3]
	v_mfma_f32_16x16x32_bf16 v[56:59], v[172:175], v[194:197], v[56:59]
	v_mfma_f32_16x16x32_bf16 v[48:51], v[180:183], v[194:197], v[48:51]
	v_mfma_f32_16x16x32_bf16 v[40:43], v[172:175], v[202:205], v[40:43]
	v_mfma_f32_16x16x32_bf16 v[32:35], v[180:183], v[202:205], v[32:35]
	v_mfma_f32_16x16x32_bf16 v[24:27], v[172:175], v[210:213], v[24:27]
	v_mfma_f32_16x16x32_bf16 v[16:19], v[180:183], v[210:213], v[16:19]
	v_mfma_f32_16x16x32_bf16 v[8:11], v[172:175], v[218:221], v[8:11]
	v_mfma_f32_16x16x32_bf16 v[0:3], v[180:183], v[218:221], v[0:3]
	s_setprio 0
	s_barrier
	s_add_i32 s69, s69, 2
	s_add_u32 s42, s42, 0x100
	s_addc_u32 s43, s43, 0
	s_add_u32 s65, s65, 0x100
	s_addc_u32 s68, s68, 0
	s_cmp_gt_u32 s69, 13
	s_cbranch_scc0 .LBB0_276
	s_and_b64 vcc, exec, s[14:15]
	s_cbranch_vccz .LBB0_279
	s_barrier

; #define ATT_SUMPACK(j) do { const float e0_ = (j) < 8 ? P0[2 * ((j) & 7)] : P1[2 * ((j) & 7)], e1_ = (j) < 8 ? P0[2 * ((j) & 7) + 1] : P1[2 * ((j) & 7) + 1]; \
;         if ((j) & 1) { rc += e0_; rd += e1_; } else { ra += e0_; rb += e1_; } S.pw[j] = cvtpk(e0_, e1_); } while (0)
; template <int GRP, bool has_next> __device__ __forceinline__ void att_step(const AttCtx<GRP>& C, AttState<GRP>& S, int s, f32x16& P0, f32x16& P1, f32x16& PN0, f32x16& PN1, u32x4& kreg, u32x4& preg, u32x4& vreg) {
;     ...
;     constexpr int NE = NKS - 1;
;     float ra = 0.f, rb = 0.f, rc = 0.f, rd = 0.f;
;     ...
; #pragma unroll
;     for (int c = 1; c < NKS; ++c) {
;         if (has_next) {
;             if (c == NK0) att_kfrag<GRP, NK0, NK1>(C, (s + 1) & 1, kfb);
;             const bf16x8 a0 = c < NK0 ? kfa[2 * c] : kfb[2 * (c - NK0)], a1 = c < NK0 ? kfa[2 * c + 1] : kfb[2 * (c - NK0) + 1];
;             PN0 = __builtin_amdgcn_mfma_f32_32x32x16_bf16(a0, S.qr[c], PN0, 0, 0, 0); PN1 = __builtin_amdgcn_mfma_f32_32x32x16_bf16(a1, S.qr[c], PN1, 0, 0, 0);
;         }
; #pragma unroll
;         for (int j = (c - 1) * 16 / NE; j < c * 16 / NE; ++j) {
;             if (j < 8) { P0[2 * j] = __builtin_amdgcn_exp2f(P0[2 * j]); P0[2 * j + 1] = __builtin_amdgcn_exp2f(P0[2 * j + 1]); }
;             else { P1[2 * (j - 8)] = __builtin_amdgcn_exp2f(P1[2 * (j - 8)]); P1[2 * (j - 8) + 1] = __builtin_amdgcn_exp2f(P1[2 * (j - 8) + 1]); }
;         }
;         if (c > 1) {
; #pragma unroll
;             for (int j = (c - 2) * 16 / NE; j < (c - 1) * 16 / NE; ++j) ATT_SUMPACK(j);
;         }
;         __builtin_amdgcn_sched_barrier(0);
;     }
;     if (has_next && S.refnz && t != 63) { PN0 = __builtin_amdgcn_mfma_f32_32x32x16_bf16(ones, qx, PN0, 0, 0, 0); PN1 = __builtin_amdgcn_mfma_f32_32x32x16_bf16(ones, qx, PN1, 0, 0, 0); }
;     att_vfrag<GRP>(C, s & 1, vf);
; #pragma unroll
;     for (int j = (NE - 1) * 16 / NE; j < 16; ++j) ATT_SUMPACK(j);
;     ...
;     S.lrun += (ra + rb) + (rc + rd);
.Lmla_nomax1:
	v_exp_f32_e32 v48, v48
	v_exp_f32_e32 v49, v49
	v_exp_f32_e32 v50, v50
	v_exp_f32_e32 v51, v51
	v_cvt_pk_bf16_f32 v216, v48, v49
	v_exp_f32_e32 v52, v52
	v_exp_f32_e32 v53, v53
	v_cvt_pk_bf16_f32 v217, v50, v51
	v_exp_f32_e32 v54, v54
	v_exp_f32_e32 v55, v55
	v_add_f32_e32 v248, v48, v52
	v_add_f32_e32 v249, v49, v53
	v_cvt_pk_bf16_f32 v218, v52, v53
	v_exp_f32_e32 v56, v56
	v_exp_f32_e32 v57, v57
	v_add_f32_e32 v250, v50, v54
	v_add_f32_e32 v251, v51, v55
	v_cvt_pk_bf16_f32 v219, v54, v55
	v_exp_f32_e32 v58, v58
	v_exp_f32_e32 v59, v59
	v_add_f32_e32 v248, v248, v56
	v_add_f32_e32 v249, v249, v57
	v_cvt_pk_bf16_f32 v220, v56, v57
	v_exp_f32_e32 v60, v60
	v_exp_f32_e32 v61, v61
	v_add_f32_e32 v250, v250, v58
	v_add_f32_e32 v251, v251, v59
	v_cvt_pk_bf16_f32 v221, v58, v59
	v_exp_f32_e32 v62, v62
	v_exp_f32_e32 v63, v63
	v_add_f32_e32 v248, v248, v60
	v_add_f32_e32 v249, v249, v61
	v_cvt_pk_bf16_f32 v222, v60, v61
	v_exp_f32_e32 v32, v32
	v_exp_f32_e32 v33, v33
	v_add_f32_e32 v250, v250, v62
	v_add_f32_e32 v251, v251, v63
	v_cvt_pk_bf16_f32 v223, v62, v63
	v_exp_f32_e32 v34, v34
	v_exp_f32_e32 v35, v35
	v_add_f32_e32 v248, v248, v32
	v_add_f32_e32 v249, v249, v33
	v_cvt_pk_bf16_f32 v224, v32, v33
	v_exp_f32_e32 v36, v36
	v_exp_f32_e32 v37, v37
	v_add_f32_e32 v250, v250, v34
	v_add_f32_e32 v251, v251, v35
	v_cvt_pk_bf16_f32 v225, v34, v35
	v_exp_f32_e32 v38, v38
	v_exp_f32_e32 v39, v39
	v_add_f32_e32 v248, v248, v36
	v_add_f32_e32 v249, v249, v37
	v_cvt_pk_bf16_f32 v226, v36, v37
	v_exp_f32_e32 v40, v40
	v_exp_f32_e32 v41, v41
	v_add_f32_e32 v250, v250, v38
	v_add_f32_e32 v251, v251, v39
	v_cvt_pk_bf16_f32 v227, v38, v39
	v_exp_f32_e32 v42, v42
	v_exp_f32_e32 v43, v43
	v_add_f32_e32 v248, v248, v40
	v_add_f32_e32 v249, v249, v41
	v_cvt_pk_bf16_f32 v228, v40, v41
	v_exp_f32_e32 v44, v44
	v_exp_f32_e32 v45, v45
	v_add_f32_e32 v250, v250, v42
	v_add_f32_e32 v251, v251, v43
	v_cvt_pk_bf16_f32 v229, v42, v43
	v_exp_f32_e32 v46, v46
	v_exp_f32_e32 v47, v47
	v_add_f32_e32 v248, v248, v44
	v_add_f32_e32 v249, v249, v45
	v_cvt_pk_bf16_f32 v230, v44, v45
	v_add_f32_e32 v250, v250, v46
	v_add_f32_e32 v251, v251, v47
	v_cvt_pk_bf16_f32 v231, v46, v47
	v_add_f32_e32 v248, v248, v249
	v_add_f32_e32 v250, v250, v251
	v_add_f32_e32 v248, v248, v250
	v_add_f32_e32 v170, v170, v248
	s_branch .Lpagefit_2
	s_nop 0
	s_nop 0
	s_nop 0
	s_nop 0
	s_nop 0
	s_nop 0
	s_nop 0
	s_nop 0
	s_nop 0
	s_nop 0
	s_nop 0
	s_nop 0
	s_nop 0
	s_nop 0
	s_nop 0
	s_nop 0
	s_nop 0
	s_nop 0
	s_nop 0
	s_nop 0
	s_nop 0
	s_nop 0
	s_nop 0
	s_nop 0
	s_nop 0
	s_nop 0
	s_nop 0
	s_nop 0
	s_nop 0
	s_nop 0
	s_nop 0
	s_nop 0
	s_nop 0
	s_nop 0
	s_nop 0
	s_nop 0
	s_nop 0
	s_nop 0
	s_nop 0
	s_nop 0
	s_nop 0
	s_nop 0
	s_nop 0
	s_nop 0
	s_nop 0
	s_nop 0
	s_nop 0
	s_nop 0
	s_nop 0
	s_nop 0
	s_nop 0
	s_nop 0
	s_nop 0
	s_nop 0
	s_nop 0
	s_nop 0
	s_nop 0
	s_nop 0
	s_nop 0
	s_nop 0
	s_nop 0
	s_nop 0
	s_nop 0
	s_nop 0
	s_nop 0
	s_nop 0
	s_nop 0
	s_nop 0
	s_nop 0
	s_nop 0
	s_nop 0
	s_nop 0
	s_nop 0
	s_nop 0
	s_nop 0
	s_nop 0
	s_nop 0
	s_nop 0
	s_nop 0
	s_nop 0
	s_nop 0
	s_nop 0
	s_nop 0
	s_nop 0
	s_nop 0
	s_nop 0
	s_nop 0
	s_nop 0
	s_nop 0
	s_nop 0
	s_nop 0
	s_nop 0
	s_nop 0
	s_nop 0
	s_nop 0
	s_nop 0
	s_nop 0
	s_nop 0
	s_nop 0
	s_nop 0
	s_nop 0
	s_nop 0
	s_nop 0
	s_nop 0
	s_nop 0
	s_nop 0
	s_nop 0
	s_nop 0
	s_nop 0
	s_nop 0
	s_nop 0
	s_nop 0
	s_nop 0
	s_nop 0
	s_nop 0
	s_nop 0
	s_nop 0
	s_nop 0
	s_nop 0
	s_nop 0
	s_nop 0
	s_nop 0
	s_nop 0
	s_nop 0
	s_nop 0
	s_nop 0
	s_nop 0
	s_nop 0
	s_nop 0
	s_nop 0
	s_nop 0
	s_nop 0
	s_nop 0
	s_nop 0
	s_nop 0
	s_nop 0
	s_nop 0
	s_nop 0
	s_nop 0
	s_nop 0
	s_nop 0
	s_nop 0
	s_nop 0
	s_nop 0
	s_nop 0
	s_nop 0
	s_nop 0
	s_nop 0
	s_nop 0
	s_nop 0
	s_nop 0
	s_nop 0
	s_nop 0
	s_nop 0
	s_nop 0
	s_nop 0
	s_nop 0
	s_nop 0
	s_nop 0
	s_nop 0
	s_nop 0
	s_nop 0
	s_nop 0
	s_nop 0
	s_nop 0
	s_nop 0
	s_nop 0
	s_nop 0
	s_nop 0
	s_nop 0
	s_nop 0
	s_nop 0
	s_nop 0
	s_nop 0
	s_nop 0
	s_nop 0
	s_nop 0
	s_nop 0
	s_nop 0
	s_nop 0
	s_nop 0
	s_nop 0
	s_nop 0
	s_nop 0
	s_nop 0
	s_nop 0
	s_nop 0
	s_nop 0
	s_nop 0
	s_nop 0
	s_nop 0
	s_nop 0
	s_nop 0
	s_nop 0
	s_nop 0
	s_nop 0
	s_nop 0
	s_nop 0
	s_nop 0
	s_nop 0
	s_nop 0
	s_nop 0
	s_nop 0
	s_nop 0
	s_nop 0
	s_nop 0
	s_nop 0
	s_nop 0
	s_nop 0
	s_nop 0
	s_nop 0
	s_nop 0
	s_nop 0
	s_nop 0
	s_nop 0
	s_nop 0
	s_nop 0
	s_nop 0
	s_nop 0
	s_nop 0
	s_nop 0
	s_nop 0
	s_nop 0
	s_nop 0
	s_nop 0
	s_nop 0
	s_nop 0
	s_nop 0
	s_nop 0
	s_nop 0
	s_nop 0
	s_nop 0
	s_nop 0
	s_nop 0
	s_nop 0
	s_nop 0
	s_nop 0
	s_nop 0
	s_nop 0
	s_nop 0
	s_nop 0
	s_nop 0
	s_nop 0
	s_nop 0
	s_nop 0
	s_nop 0
	s_nop 0
	s_nop 0
	s_nop 0
	s_nop 0
	s_nop 0
	s_nop 0
	s_nop 0
	s_nop 0
	s_nop 0
	s_nop 0
	s_nop 0
	s_nop 0
	s_nop 0
	s_nop 0
	s_nop 0
	s_nop 0
	s_nop 0
	s_nop 0
	s_nop 0
	s_nop 0
	s_nop 0
	s_nop 0
	s_nop 0
	s_nop 0
	s_nop 0
	s_nop 0
	s_nop 0
	s_nop 0
	s_nop 0
	s_nop 0
	s_nop 0
	s_nop 0
	s_nop 0
	s_nop 0
	s_nop 0
	s_nop 0
	s_nop 0
	s_nop 0
	s_nop 0
	s_nop 0
	s_nop 0
	s_nop 0
	s_nop 0
	s_nop 0
	s_nop 0
	s_nop 0
	s_nop 0
	s_nop 0
	s_nop 0
	s_nop 0
	s_nop 0
	s_nop 0
	s_nop 0
	s_nop 0
	s_nop 0
	s_nop 0
	s_nop 0
	s_nop 0
	s_nop 0
	s_nop 0
	s_nop 0
	s_nop 0
	s_nop 0
	s_nop 0
	s_nop 0
	s_nop 0
	s_nop 0
	s_nop 0
	s_nop 0
	s_nop 0
	s_nop 0
	s_nop 0
	s_nop 0
	s_nop 0
	s_nop 0
	s_nop 0
	s_nop 0
	s_nop 0
	s_nop 0
	s_nop 0
	s_nop 0
	s_nop 0
	s_nop 0
	s_nop 0
	s_nop 0
	s_nop 0
	s_nop 0
	s_nop 0
	s_nop 0
	s_nop 0
	s_nop 0
	s_nop 0
	s_nop 0
	s_nop 0
	s_nop 0
	s_nop 0
	s_nop 0
	s_nop 0
	s_nop 0
	s_nop 0
	s_nop 0
	s_nop 0
	s_nop 0
	s_nop 0
	s_nop 0
	s_nop 0
	s_nop 0
	s_nop 0
	s_nop 0
	s_nop 0
	s_nop 0
	s_nop 0
	s_nop 0
	s_nop 0
	s_nop 0
	s_nop 0
	s_nop 0
	s_nop 0
	s_nop 0
	s_nop 0
	s_nop 0
	s_nop 0
	s_nop 0
	s_nop 0
	s_nop 0
	s_nop 0
	s_nop 0
	s_nop 0
	s_nop 0
	s_nop 0
	s_nop 0
	s_nop 0
	s_nop 0
	s_nop 0
	s_nop 0
	s_nop 0
	s_nop 0
	s_nop 0
	s_nop 0
	s_nop 0
	s_nop 0
	s_nop 0
	s_nop 0
	s_nop 0
	s_nop 0
	s_nop 0
	s_nop 0
	s_nop 0
	s_nop 0
	s_nop 0
	s_nop 0
	s_nop 0
	s_nop 0
	s_nop 0
	s_nop 0
	s_nop 0
	s_nop 0
	s_nop 0
	s_nop 0
	s_nop 0
	s_nop 0
	s_nop 0
	s_nop 0
	s_nop 0
	s_nop 0
	s_nop 0
	s_nop 0
	s_nop 0
	s_nop 0
	s_nop 0
	s_nop 0
	s_nop 0
	s_nop 0
	s_nop 0
	s_nop 0
	s_nop 0
	s_nop 0
	s_nop 0
	s_nop 0
	s_nop 0
	s_nop 0
	s_nop 0
	s_nop 0
	s_nop 0
	s_nop 0
	s_nop 0
	s_nop 0
	s_nop 0
	s_nop 0
	s_nop 0
	s_nop 0
	s_nop 0
	s_nop 0
	s_nop 0
	s_nop 0
	s_nop 0
	s_nop 0
	s_nop 0
	s_nop 0
	s_nop 0
	s_nop 0
	s_nop 0
	s_nop 0
	s_nop 0
	s_nop 0
	s_nop 0
	s_nop 0
	s_nop 0
	s_nop 0
	s_nop 0
	s_nop 0
	s_nop 0
	s_nop 0
	s_nop 0
	s_nop 0
	s_nop 0
	s_nop 0
	s_nop 0
	s_nop 0
	s_nop 0
	s_nop 0
	s_nop 0
	s_nop 0
	s_nop 0
	s_nop 0
	s_nop 0
	s_nop 0
	s_nop 0
	s_nop 0
	s_nop 0
	s_nop 0
	s_nop 0
	s_nop 0
	s_nop 0
	s_nop 0
	s_nop 0
	s_nop 0
	s_nop 0
	s_nop 0
	s_nop 0
	s_nop 0
	s_nop 0
	s_nop 0
	s_nop 0
	s_nop 0
	s_nop 0
	s_nop 0
	s_nop 0
	s_nop 0
	s_nop 0
	s_nop 0
	s_nop 0
	s_nop 0
	s_nop 0
	s_nop 0
	s_nop 0
	s_nop 0
	s_nop 0
	s_nop 0
	s_nop 0
	s_nop 0
	s_nop 0
; #define ATT_SUMPACK(j) do { const float e0_ = (j) < 8 ? P0[2 * ((j) & 7)] : P1[2 * ((j) & 7)], e1_ = (j) < 8 ? P0[2 * ((j) & 7) + 1] : P1[2 * ((j) & 7) + 1]; \
;         if ((j) & 1) { rc += e0_; rd += e1_; } else { ra += e0_; rb += e1_; } S.pw[j] = cvtpk(e0_, e1_); } while (0)
; template <int GRP, bool has_next> __device__ __forceinline__ void att_step(const AttCtx<GRP>& C, AttState<GRP>& S, int s, f32x16& P0, f32x16& P1, f32x16& PN0, f32x16& PN1, u32x4& kreg, u32x4& preg, u32x4& vreg) {
;     ...
;         att_kfrag<GRP, 0, NK0>(C, (s + 1) & 1, kfa);
;     }
;     if (has_next) { PN0 = __builtin_amdgcn_mfma_f32_32x32x16_bf16(kfa[0], S.qr[0], (f32x16){}, 0, 0, 0); PN1 = __builtin_amdgcn_mfma_f32_32x32x16_bf16(kfa[1], S.qr[0], (f32x16){}, 0, 0, 0); }
;     ...
;     for (int c = 1; c < NKS; ++c) {
;         if (has_next) {
;             if (c == NK0) att_kfrag<GRP, NK0, NK1>(C, (s + 1) & 1, kfb);
;             const bf16x8 a0 = c < NK0 ? kfa[2 * c] : kfb[2 * (c - NK0)], a1 = c < NK0 ? kfa[2 * c + 1] : kfb[2 * (c - NK0) + 1];
;             PN0 = __builtin_amdgcn_mfma_f32_32x32x16_bf16(a0, S.qr[c], PN0, 0, 0, 0); PN1 = __builtin_amdgcn_mfma_f32_32x32x16_bf16(a1, S.qr[c], PN1, 0, 0, 0);
;         }
; #pragma unroll
;         for (int j = (c - 1) * 16 / NE; j < c * 16 / NE; ++j) {
;             if (j < 8) { P0[2 * j] = __builtin_amdgcn_exp2f(P0[2 * j]); P0[2 * j + 1] = __builtin_amdgcn_exp2f(P0[2 * j + 1]); }
;             else { P1[2 * (j - 8)] = __builtin_amdgcn_exp2f(P1[2 * (j - 8)]); P1[2 * (j - 8) + 1] = __builtin_amdgcn_exp2f(P1[2 * (j - 8) + 1]); }
;         }
;         if (c > 1) {
; #pragma unroll
;             for (int j = (c - 2) * 16 / NE; j < (c - 1) * 16 / NE; ++j) ATT_SUMPACK(j);
;         }
;         __builtin_amdgcn_sched_barrier(0);
;     }
;     if (has_next && S.refnz && t != 63) { PN0 = __builtin_amdgcn_mfma_f32_32x32x16_bf16(ones, qx, PN0, 0, 0, 0); PN1 = __builtin_amdgcn_mfma_f32_32x32x16_bf16(ones, qx, PN1, 0, 0, 0); }
.Lpagefit_2:
.Lmla_L_loop:
	ds_read_b128 v[136:139], v174 offset:13312
	ds_read_b128 v[140:143], v174 offset:19968
	ds_read_b128 v[144:147], v174 offset:13344
	ds_read_b128 v[148:151], v174 offset:20000
	ds_read_b128 v[176:179], v174 offset:13376
	ds_read_b128 v[180:183], v174 offset:20032
	s_waitcnt lgkmcnt(5)
	v_mfma_f32_32x32x16_bf16 v[80:95], v[136:139], v[128:131], 0
	ds_read_b128 v[136:139], v174 offset:13408
	s_waitcnt lgkmcnt(5)
	v_mfma_f32_32x32x16_bf16 v[64:79], v[140:143], v[128:131], 0
	ds_read_b128 v[140:143], v174 offset:20064
	s_waitcnt lgkmcnt(5)
	v_mfma_f32_32x32x16_bf16 v[80:95], v[144:147], v[124:127], v[80:95]
	ds_read_b128 v[144:147], v174 offset:13440
	s_waitcnt lgkmcnt(5)
	v_mfma_f32_32x32x16_bf16 v[64:79], v[148:151], v[124:127], v[64:79]
	ds_read_b128 v[148:151], v174 offset:20096
	s_waitcnt lgkmcnt(5)
	v_mfma_f32_32x32x16_bf16 v[80:95], v[176:179], v[120:123], v[80:95]
	ds_read_b128 v[176:179], v174 offset:13472
	s_waitcnt lgkmcnt(5)
	v_mfma_f32_32x32x16_bf16 v[64:79], v[180:183], v[120:123], v[64:79]
	ds_read_b128 v[180:183], v174 offset:20128
	s_waitcnt lgkmcnt(5)
	v_mfma_f32_32x32x16_bf16 v[80:95], v[136:139], v[116:119], v[80:95]
	ds_read_b128 v[232:235], v157 offset:26624
	s_waitcnt lgkmcnt(5)
	v_mfma_f32_32x32x16_bf16 v[64:79], v[140:143], v[116:119], v[64:79]
	ds_read_b128 v[236:239], v157 offset:31232
	s_waitcnt lgkmcnt(5)
	v_mfma_f32_32x32x16_bf16 v[80:95], v[144:147], v[112:115], v[80:95]
	ds_read_b128 v[240:243], v157 offset:26656
	s_waitcnt lgkmcnt(5)
	v_mfma_f32_32x32x16_bf16 v[64:79], v[148:151], v[112:115], v[64:79]
	ds_read_b128 v[244:247], v157 offset:31264
	s_waitcnt lgkmcnt(5)
	v_mfma_f32_32x32x16_bf16 v[80:95], v[176:179], v[108:111], v[80:95]
	s_waitcnt lgkmcnt(4)
	v_mfma_f32_32x32x16_bf16 v[64:79], v[180:183], v[108:111], v[64:79]
	s_cmp_eq_u32 s72, 0
	s_cbranch_scc1 .Lmla_nrz3
	v_xor_b32_e32 v195, 0x80000000, v175
	s_mov_b32 s18, s16
	s_mov_b32 s19, s16
	s_mov_b32 s17, s16
	v_mov_b64_e32 v[186:187], s[18:19]
	v_mov_b64_e32 v[184:185], s[16:17]
	s_mov_b64 vcc, s[0:1]
	v_cndmask_b32_sdwa v96, v97, v195, vcc dst_sel:DWORD dst_unused:UNUSED_PAD src0_sel:DWORD src1_sel:WORD_1
	v_mov_b32_e32 v98, v97
	v_mov_b32_e32 v99, v97
	s_nop 1
	v_mfma_f32_32x32x16_bf16 v[80:95], v[184:187], v[96:99], v[80:95]
	v_mfma_f32_32x32x16_bf16 v[64:79], v[184:187], v[96:99], v[64:79]

; template <int GRP> ...
;     ...
;     if (wid >= 4) __builtin_amdgcn_s_setprio(1);
;     asm volatile("s_nop 15\n\ts_nop 7" : "+v"(pa0), "+v"(pa1));
;     for (int s = 0; s < NSTEP - 2; s += 2) { att_step<GRP, true>(C, S, s, pa0, pa1, pb0, pb1, kA, pA, vA); att_step<GRP, true>(C, S, s + 1, pb0, pb1, pa0, pa1, kA, pA, vA); }
.Lmla_T_entry:
	s_setprio 1
	s_branch .Lpagefit_3
	s_nop 0
	s_nop 0
	s_nop 0
	s_nop 0
	s_nop 0
	s_nop 0
	s_nop 0
	s_nop 0
	s_nop 0
	s_nop 0
	s_nop 0
	s_nop 0
	s_nop 0
	s_nop 0
	s_nop 0
	s_nop 0
	s_nop 0
	s_nop 0
	s_nop 0
	s_nop 0
	s_nop 0
	s_nop 0
	s_nop 0
	s_nop 0
	s_nop 0
	s_nop 0
	s_nop 0
	s_nop 0
	s_nop 0
	s_nop 0
	s_nop 0
	s_nop 0
	s_nop 0
	s_nop 0
	s_nop 0
	s_nop 0
	s_nop 0
	s_nop 0
	s_nop 0
	s_nop 0
	s_nop 0
	s_nop 0
	s_nop 0
	s_nop 0
	s_nop 0
	s_nop 0
	s_nop 0
	s_nop 0
	s_nop 0
	s_nop 0
	s_nop 0
	s_nop 0
	s_nop 0
	s_nop 0
	s_nop 0
	s_nop 0
	s_nop 0
	s_nop 0
	s_nop 0
	s_nop 0
	s_nop 0
	s_nop 0
	s_nop 0
	s_nop 0
	s_nop 0
	s_nop 0
	s_nop 0
	s_nop 0
	s_nop 0
	s_nop 0
	s_nop 0
	s_nop 0
	s_nop 0
	s_nop 0
	s_nop 0
	s_nop 0
	s_nop 0
	s_nop 0
	s_nop 0
	s_nop 0
	s_nop 0
	s_nop 0
	s_nop 0
	s_nop 0
	s_nop 0
	s_nop 0
	s_nop 0
	s_nop 0
	s_nop 0
	s_nop 0
	s_nop 0
	s_nop 0
	s_nop 0
	s_nop 0
	s_nop 0
	s_nop 0
	s_nop 0
	s_nop 0
	s_nop 0
	s_nop 0
	s_nop 0
	s_nop 0
	s_nop 0
	s_nop 0
	s_nop 0
	s_nop 0
	s_nop 0
	s_nop 0
	s_nop 0
	s_nop 0
	s_nop 0
	s_nop 0
	s_nop 0
	s_nop 0
	s_nop 0
	s_nop 0
	s_nop 0
	s_nop 0
	s_nop 0
	s_nop 0
	s_nop 0
	s_nop 0
	s_nop 0
	s_nop 0
	s_nop 0
	s_nop 0
	s_nop 0
	s_nop 0
	s_nop 0
	s_nop 0
	s_nop 0
	s_nop 0
	s_nop 0
	s_nop 0
	s_nop 0
	s_nop 0
	s_nop 0
	s_nop 0
	s_nop 0
	s_nop 0
	s_nop 0
	s_nop 0
	s_nop 0
	s_nop 0
	s_nop 0
	s_nop 0
	s_nop 0
	s_nop 0
	s_nop 0
	s_nop 0
	s_nop 0
	s_nop 0
	s_nop 0
	s_nop 0
	s_nop 0
	s_nop 0
	s_nop 0
	s_nop 0
	s_nop 0
	s_nop 0
	s_nop 0
	s_nop 0
	s_nop 0
	s_nop 0
	s_nop 0
	s_nop 0
	s_nop 0
	s_nop 0
	s_nop 0
	s_nop 0
	s_nop 0
	s_nop 0
	s_nop 0
	s_nop 0
	s_nop 0
	s_nop 0
	s_nop 0
	s_nop 0
	s_nop 0
	s_nop 0
	s_nop 0
	s_nop 0
	s_nop 0
	s_nop 0
	s_nop 0
	s_nop 0
	s_nop 0
	s_nop 0
	s_nop 0
	s_nop 0
	s_nop 0
	s_nop 0
	s_nop 0
	s_nop 0
	s_nop 0
	s_nop 0
	s_nop 0
	s_nop 0
	s_nop 0
	s_nop 0
	s_nop 0
	s_nop 0
	s_nop 0
	s_nop 0
	s_nop 0
	s_nop 0
	s_nop 0
	s_nop 0
	s_nop 0
	s_nop 0
	s_nop 0
	s_nop 0
	s_nop 0
	s_nop 0
	s_nop 0
	s_nop 0
	s_nop 0
	s_nop 0
	s_nop 0
	s_nop 0
	s_nop 0
	s_nop 0
	s_nop 0
	s_nop 0
	s_nop 0
	s_nop 0
	s_nop 0
	s_nop 0
	s_nop 0
	s_nop 0
	s_nop 0
	s_nop 0
	s_nop 0
	s_nop 0
	s_nop 0
	s_nop 0
	s_nop 0
	s_nop 0
	s_nop 0
	s_nop 0
	s_nop 0
	s_nop 0
	s_nop 0
	s_nop 0
	s_nop 0
	s_nop 0
	s_nop 0
	s_nop 0
	s_nop 0
	s_nop 0
	s_nop 0
	s_nop 0
	s_nop 0
	s_nop 0
	s_nop 0
	s_nop 0
	s_nop 0
	s_nop 0
	s_nop 0
	s_nop 0
	s_nop 0
	s_nop 0
	s_nop 0
	s_nop 0
	s_nop 0
	s_nop 0
	s_nop 0
	s_nop 0
	s_nop 0
	s_nop 0
	s_nop 0
	s_nop 0
	s_nop 0
	s_nop 0
	s_nop 0
	s_nop 0
	s_nop 0
	s_nop 0
	s_nop 0
	s_nop 0
	s_nop 0
	s_nop 0
	s_nop 0
	s_nop 0
	s_nop 0
	s_nop 0
	s_nop 0
	s_nop 0
	s_nop 0
	s_nop 0
	s_nop 0
	s_nop 0
	s_nop 0
	s_nop 0
	s_nop 0
	s_nop 0
	s_nop 0
	s_nop 0
	s_nop 0
	s_nop 0
	s_nop 0
	s_nop 0
	s_nop 0
	s_nop 0
	s_nop 0
	s_nop 0
	s_nop 0
	s_nop 0
	s_nop 0
	s_nop 0
	s_nop 0
	s_nop 0
	s_nop 0
	s_nop 0
	s_nop 0
	s_nop 0
	s_nop 0
	s_nop 0
	s_nop 0
	s_nop 0
	s_nop 0
	s_nop 0
	s_nop 0
	s_nop 0
	s_nop 0
	s_nop 0
	s_nop 0
	s_nop 0
	s_nop 0
	s_nop 0
	s_nop 0
	s_nop 0
	s_nop 0
	s_nop 0
	s_nop 0
	s_nop 0
	s_nop 0
	s_nop 0
	s_nop 0
	s_nop 0
	s_nop 0
	s_nop 0
	s_nop 0
	s_nop 0
	s_nop 0
	s_nop 0
	s_nop 0
	s_nop 0
	s_nop 0
	s_nop 0
	s_nop 0
	s_nop 0
	s_nop 0
	s_nop 0
	s_nop 0
	s_nop 0
	s_nop 0
	s_nop 0
	s_nop 0
	s_nop 0
	s_nop 0
	s_nop 0
	s_nop 0
	s_nop 0
	s_nop 0
	s_nop 0
	s_nop 0
	s_nop 0
	s_nop 0
	s_nop 0
	s_nop 0
	s_nop 0
	s_nop 0
	s_nop 0
	s_nop 0
	s_nop 0
	s_nop 0
	s_nop 0
	s_nop 0
	s_nop 0
	s_nop 0
	s_nop 0
	s_nop 0
	s_nop 0
	s_nop 0
	s_nop 0
	s_nop 0
	s_nop 0
	s_nop 0
	s_nop 0
	s_nop 0
	s_nop 0
	s_nop 0
	s_nop 0
	s_nop 0
	s_nop 0
	s_nop 0
	s_nop 0
	s_nop 0
	s_nop 0
	s_nop 0
	s_nop 0
	s_nop 0
	s_nop 0
	s_nop 0
	s_nop 0
	s_nop 0
	s_nop 0
	s_nop 0
	s_nop 0
	s_nop 0
	s_nop 0
	s_nop 0
	s_nop 0
	s_nop 0
	s_nop 0
	s_nop 0
	s_nop 0
	s_nop 0
	s_nop 0
	s_nop 0
	s_nop 0
	s_nop 0
	s_nop 0
	s_nop 0
	s_nop 0
	s_nop 0
	s_nop 0
	s_nop 0
	s_nop 0
	s_nop 0
	s_nop 0
	s_nop 0
	s_nop 0
	s_nop 0
	s_nop 0
	s_nop 0
	s_nop 0
	s_nop 0
	s_nop 0
	s_nop 0
	s_nop 0
	s_nop 0
	s_nop 0
	s_nop 0
	s_nop 0
	s_nop 0
	s_nop 0
	s_nop 0
	s_nop 0
	s_nop 0
	s_nop 0
	s_nop 0
	s_nop 0
	s_nop 0
	s_nop 0
	s_nop 0
	s_nop 0
	s_nop 0
	s_nop 0
	s_nop 0
	s_nop 0
	s_nop 0
	s_nop 0
	s_nop 0
	s_nop 0
	s_nop 0
	s_nop 0
	s_nop 0
	s_nop 0
	s_nop 0
	s_nop 0
	s_nop 0
	s_nop 0
	s_nop 0
	s_nop 0
	s_nop 0
	s_nop 0
	s_nop 0
	s_nop 0
	s_nop 0
	s_nop 0
	s_nop 0
	s_nop 0
	s_nop 0
	s_nop 0
	s_nop 0
	s_nop 0
	s_nop 0
	s_nop 0
	s_nop 0
	s_nop 0
	s_nop 0
	s_nop 0
	s_nop 0
	s_nop 0
	s_nop 0
	s_nop 0
	s_nop 0
	s_nop 0
	s_nop 0
	s_nop 0
	s_nop 0
	s_nop 0
	s_nop 0
	s_nop 0
	s_nop 0
	s_nop 0
	s_nop 0
	s_nop 0
	s_nop 0
	s_nop 0
	s_nop 0
	s_nop 0
	s_nop 0
	s_nop 0
	s_nop 0
	s_nop 0
	s_nop 0
	s_nop 0
	s_nop 0
	s_nop 0
	s_nop 0
	s_nop 0
	s_nop 0
	s_nop 0
	s_nop 0
	s_nop 0
	s_nop 0
	s_nop 0
	s_nop 0
	s_nop 0
	s_nop 0
	s_nop 0
	s_nop 0
	s_nop 0
	s_nop 0
	s_nop 0
	s_nop 0
	s_nop 0
	s_nop 0
	s_nop 0
	s_nop 0
	s_nop 0
	s_nop 0
	s_nop 0
	s_nop 0
	s_nop 0
	s_nop 0
	s_nop 0
	s_nop 0
	s_nop 0
	s_nop 0
	s_nop 0
	s_nop 0
	s_nop 0
	s_nop 0
	s_nop 0
	s_nop 0
	s_nop 0
	s_nop 0
	s_nop 0
	s_nop 0
	s_nop 0
	s_nop 0
	s_nop 0
	s_nop 0
	s_nop 0
	s_nop 0
	s_nop 0
	s_nop 0
	s_nop 0
	s_nop 0
	s_nop 0
	s_nop 0
	s_nop 0
	s_nop 0
	s_nop 0
	s_nop 0
	s_nop 0
	s_nop 0
	s_nop 0
	s_nop 0
	s_nop 0
	s_nop 0
	s_nop 0
	s_nop 0
	s_nop 0
	s_nop 0
	s_nop 0
	s_nop 0
	s_nop 0
	s_nop 0
	s_nop 0
	s_nop 0
	s_nop 0
	s_nop 0
	s_nop 0
	s_nop 0
	s_nop 0
	s_nop 0
	s_nop 0
	s_nop 0
	s_nop 0
	s_nop 0
	s_nop 0
	s_nop 0
	s_nop 0
	s_nop 0
	s_nop 0
	s_nop 0
	s_nop 0
	s_nop 0
	s_nop 0
	s_nop 0
	s_nop 0
	s_nop 0
	s_nop 0
	s_nop 0
	s_nop 0
	s_nop 0
	s_nop 0
	s_nop 0
	s_nop 0
	s_nop 0
	s_nop 0
	s_nop 0
	s_nop 0
	s_nop 0
	s_nop 0
	s_nop 0
	s_nop 0
	s_nop 0
	s_nop 0
	s_nop 0
	s_nop 0
	s_nop 0
	s_nop 0
	s_nop 0
	s_nop 0
	s_nop 0
	s_nop 0
	s_nop 0
	s_nop 0
	s_nop 0
	s_nop 0
	s_nop 0
	s_nop 0
	s_nop 0
	s_nop 0
; #define LAS __attribute__((address_space(3)))
; __device__ __forceinline__ float xhalf_max(float m) { auto rr = __builtin_amdgcn_permlane32_swap(__float_as_uint(m), __float_as_uint(m), false, false); return fmaxf(__uint_as_float(rr[0]), __uint_as_float(rr[1])); }
; __device__ __forceinline__ float max3f(float a, float b, float c) { float r; asm("v_max3_f32 %0, %1, %2, %3" : "=v"(r) : "v"(a), "v"(b), "v"(c)); return r; }
; __device__ __forceinline__ float max2f(float a, float b) { float r; asm("v_max_f32_e32 %0, %1, %2" : "=v"(r) : "v"(a), "v"(b)); return r; }
; template <int GRP> __device__ __forceinline__ void att_stk(const AttCtx<GRP>& C, int buf, const u32x4& kreg, const u32x4& preg) {
;     *(LAS u32x4*)(C.lds + buf * KBUF + C.kwo) = kreg; if (GRP == 0 && C.tid < 256) *(LAS u32x4*)(C.lds + buf * KBUF + C.pwo) = preg;
; }
; template <int GRP> __device__ __forceinline__ void att_stld(const AttCtx<GRP>& C, int s, u32x4& kreg, u32x4& preg, u32x4& vreg) {
;     constexpr int NSTEP = 256;
;     if (s + 2 < NSTEP) att_stk<GRP>(C, s & 1, kreg, preg);
;     if (s + 1 < NSTEP) att_stv<GRP>(C, (s + 1) & 1, vreg);
;     if (s + 3 < NSTEP) att_ldk<GRP>(C, s + 3, kreg, preg);
;     if (s + 2 < NSTEP) att_ldv<GRP>(C, s + 2, vreg);
; }
; template <int GRP, bool has_next> __device__ __forceinline__ void att_step(const AttCtx<GRP>& C, AttState<GRP>& S, int s, f32x16& P0, f32x16& P1, f32x16& PN0, f32x16& PN1, u32x4& kreg, u32x4& preg, u32x4& vreg) {
;     ...
;     if ((t & 7) == 0) {
;         float ma = max3f(P0[0], P0[1], P0[2]), mb = max3f(P0[3], P0[4], P0[5]), mc = max3f(P1[0], P1[1], P1[2]), md = max3f(P1[3], P1[4], P1[5]);
;         ma = max3f(ma, P0[6], P0[7]); mb = max3f(mb, P0[8], P0[9]); mc = max3f(mc, P1[6], P1[7]); md = max3f(md, P1[8], P1[9]);
;         ma = max3f(ma, P0[10], P0[11]); mb = max3f(mb, P0[12], P0[13]); mc = max3f(mc, P1[10], P1[11]); md = max3f(md, P1[12], P1[13]);
;         ma = max3f(ma, P0[14], P0[15]); mc = max3f(mc, P1[14], P1[15]); ma = max3f(ma, mb, mc); mb = md;
;         const float mx = xhalf_max(max2f(ma, mb));
;         const int up = __any(mx > THR), dn = (t == 0) ? __any(mx < -THR) : 0;
.Lpagefit_3:
.LBB0_776:
	s_waitcnt vmcnt(1)
	ds_write_b128 v171, v[104:107]
	s_mov_b32 s84, 0xfe000000
	s_mov_b32 s85, -1
	s_waitcnt vmcnt(0)
	ds_write_b128 v169, v[132:135] offset:35840
	v_lshl_add_u64 v[192:193], v[166:167], 0, s[84:85]
	global_load_dwordx4 v[104:107], v[192:193], off
	s_mov_b32 s84, 0xffffe000
	s_nop 0
	v_lshl_add_u64 v[192:193], v[166:167], 0, s[84:85]
	global_load_dwordx4 v[132:135], v[192:193], off
	s_and_b32 s10, s69, 6
	s_cmp_lg_u32 s10, 0
	s_cbranch_scc1 .Lmla_nomax13
	v_max3_f32 v96, v48, v49, v50
	v_max3_f32 v99, v32, v33, v34
	v_max3_f32 v98, v51, v52, v53
	v_max3_f32 v252, v35, v36, v37
	s_and_b32 s14, s69, 56
	v_max3_f32 v96, v96, v54, v55
	v_max3_f32 v99, v99, v38, v39
	v_max3_f32 v98, v98, v56, v57
	v_max3_f32 v252, v252, v40, v41
	s_cmp_eq_u32 s14, 0
	v_max3_f32 v96, v96, v58, v59
	v_max3_f32 v99, v99, v42, v43
	v_max3_f32 v98, v98, v60, v61
	v_max3_f32 v252, v252, v44, v45
	s_cselect_b64 s[10:11], -1, 0
	v_max3_f32 v96, v96, v62, v63
	v_max3_f32 v99, v99, v46, v47
	s_cmp_lg_u32 s14, 0
	v_max3_f32 v96, v96, v98, v99
	s_nop 0
	v_max_f32_e32 v96, v96, v252
	s_nop 0
	v_mov_b32_e32 v98, v96
	s_nop 1
	v_permlane32_swap_b32_e32 v96, v98
	v_max_f32_e32 v98, v98, v98
	v_max_f32_e32 v96, v96, v96
	v_max_f32_e32 v96, v96, v98
	v_cmp_lt_f32_e32 vcc, s54, v96
	v_mov_b32_e32 v98, 0
	s_cbranch_scc1 .Lmla_mx14
	v_cmp_gt_f32_e64 s[14:15], s55, v96
	s_cmp_lg_u64 s[14:15], 0
	s_cselect_b64 s[14:15], -1, 0
	v_cndmask_b32_e64 v98, 0, 1, s[14:15]

; template <int GRP> ...
;     constexpr int DK = GRP == 0 ? 96 : 64, NKS = DK / 16, QP = GRP == 0 ? 768 : 512, NSTEP = 4 * 64;
;     int tid_ = threadIdx.x; asm volatile("" : "+v"(tid_));
;     const int tid = tid_, lane = tid & 63, r32 = lane & 31, hi = lane >> 5, wid = __builtin_amdgcn_readfirstlane(tid >> 6);
;     AttCtx<GRP> C;
;     C.b = b; C.h0 = 4 * hh; C.lds = lds; C.Q = Q; C.KN = KN; C.KPE = KPE; C.VT = VT; C.O = O; C.tid = tid; C.hi = hi; C.trail = false;
;     C.rowbase = (size_t)b * SEQL; C.qrow = C.rowbase + (size_t)qb * 256 + wid * 32 + r32;
;     const int pr = (r32 & 19) | ((r32 & 4) << 1) | ((r32 & 8) >> 1);
;     C.kro = pr * KST + hi * 16; C.vro = 2 * KBUF + r32 * VST + hi * 16;
;     C.kkey = tid >> 3; C.kc = tid & 7; C.pkey = (tid >> 2) & 63; C.pc = tid & 3;
;     { constexpr int NHK = GRP == 0 ? 8 : 2; const size_t lo = (size_t)C.kkey * 64 + C.kc * 8;
;       C.kl = KN + (size_t)(b * NHK) * 64 * 4096 + lo; C.vl = VT + (size_t)(b * NHK) * 64 * 4096 + lo; C.pl = KPE + (C.rowbase + C.pkey) * 32 + C.pc * 8; }
;     C.kwo = C.kkey * KST + C.kc * 16; C.pwo = C.pkey * KST + 128 + C.pc * 16; C.vwo = 2 * KBUF + C.kkey * VST + C.kc * 16;
;     u32x4 kA, pA = {0u, 0u, 0u, 0u}, vA;
;     AttState<GRP> S;
;     S.o0 = (f32x16){}; S.o1 = (f32x16){}; S.mhat = 0.f; S.lrun = 0.f; S.ssq = 0.f; S.refnz = 0;
; #pragma unroll
;     for (int i = 0; i < 16; ++i) S.pw[i] = 0u;
;     { u32x4 kB, pB = {0u, 0u, 0u, 0u};
;       att_ldk<GRP>(C, 0, kA, pA); att_ldk<GRP>(C, 1, kB, pB); att_ldv<GRP>(C, 0, vA);
;       att_stk<GRP>(C, 0, kA, pA); att_stk<GRP>(C, 1, kB, pB); att_stv<GRP>(C, 0, vA); }
;     att_ldk<GRP>(C, 2, kA, pA); att_ldv<GRP>(C, 1, vA);
; #pragma unroll
;     for (int ks = 0; ks < NKS; ++ks) S.qr[ks] = *(const bf16x8*)(Q + C.qrow * QP + C.h0 * DK + ks * 16 + hi * 8);
;     ATT_BAR();
;     f32x16 pa0 = {}, pa1 = {}, pb0 = {}, pb1 = {};
;     {
;         bf16x8 kf[2 * NKS]; att_kfrag<GRP, 0, NKS>(C, 0, kf);
; #pragma unroll
;         for (int ks = 0; ks < NKS; ++ks) { pa0 = __builtin_amdgcn_mfma_f32_32x32x16_bf16(kf[2 * ks], S.qr[ks], pa0, 0, 0, 0); pa1 = __builtin_amdgcn_mfma_f32_32x32x16_bf16(kf[2 * ks + 1], S.qr[ks], pa1, 0, 0, 0); }
;     }
;     if (wid >= 4) __builtin_amdgcn_s_setprio(1);
;     asm volatile("s_nop 15\n\ts_nop 7" : "+v"(pa0), "+v"(pa1));
.LBB0_807:
	v_lshlrev_b32_e32 v8, 3, v3
	v_mad_u32_u24 v10, v6, s37, v96
	v_lshlrev_b64 v[6:7], 11, v[132:133]
	v_mov_b32_e32 v9, v97
	v_mad_u64_u32 v[0:1], s[6:7], v0, s37, v[2:3]
	v_lshl_add_u64 v[134:135], s[48:49], 0, v[6:7]
	v_lshlrev_b32_e32 v96, 1, v8
	v_mov_b32_e32 v152, 0
	s_mov_b32 s62, 0
	v_cmp_eq_u32_e64 s[0:1], 0, v3
	v_lshlrev_b32_e32 v136, 2, v3
	v_lshl_add_u64 v[142:143], v[134:135], 0, v[8:9]
	v_lshl_add_u64 v[144:145], v[4:5], 0, v[96:97]
	v_add_u32_e32 v146, 0, v10
	v_add_u32_e32 v147, 0, v0
	v_mov_b32_e32 v137, 0
	s_mov_b32 s61, 0
	v_mov_b32_e32 v148, 0
	v_mov_b32_e32 v0, 0
	v_mov_b32_e32 v1, v152
	v_mov_b32_e32 v2, v152
	v_mov_b32_e32 v3, v152
	v_mov_b32_e32 v4, v152
	v_mov_b32_e32 v5, v152
	v_mov_b32_e32 v6, v152
	v_mov_b32_e32 v7, v152
	v_mov_b32_e32 v8, v152
	v_mov_b32_e32 v9, v152
	v_mov_b32_e32 v10, v152
	v_mov_b32_e32 v11, v152
	v_mov_b32_e32 v12, v152
	v_mov_b32_e32 v13, v152
	v_mov_b32_e32 v14, v152
	v_mov_b32_e32 v15, v152
	v_mov_b32_e32 v16, 0
	v_mov_b32_e32 v17, v152
	v_mov_b32_e32 v18, v152
	v_mov_b32_e32 v19, v152
	v_mov_b32_e32 v20, v152
	v_mov_b32_e32 v21, v152
	v_mov_b32_e32 v22, v152
	v_mov_b32_e32 v23, v152
	v_mov_b32_e32 v24, v152
	v_mov_b32_e32 v25, v152
	v_mov_b32_e32 v26, v152
	v_mov_b32_e32 v27, v152
	v_mov_b32_e32 v28, v152
	v_mov_b32_e32 v29, v152
	v_mov_b32_e32 v30, v152
	v_mov_b32_e32 v31, v152
	s_nop 15
	s_nop 7
	s_branch .Lpagefit_4
	s_nop 0
	s_nop 0
	s_nop 0
	s_nop 0
	s_nop 0
	s_nop 0
	s_nop 0
	s_nop 0
	s_nop 0
	s_nop 0
	s_nop 0
	s_nop 0
	s_nop 0
	s_nop 0
	s_nop 0
	s_nop 0
	s_nop 0
	s_nop 0
	s_nop 0
	s_nop 0
	s_nop 0
	s_nop 0
	s_nop 0
	s_nop 0
	s_nop 0
	s_nop 0
	s_nop 0
	s_nop 0
	s_nop 0
	s_nop 0
	s_nop 0
	s_nop 0
	s_nop 0
	s_nop 0
	s_nop 0
	s_nop 0
	s_nop 0
	s_nop 0
	s_nop 0
	s_nop 0
	s_nop 0
	s_nop 0
	s_nop 0
	s_nop 0
	s_nop 0
	s_nop 0
	s_nop 0
	s_nop 0
	s_nop 0
	s_nop 0
	s_nop 0
	s_nop 0
	s_nop 0
	s_nop 0
	s_nop 0
	s_nop 0
	s_nop 0
	s_nop 0
	s_nop 0
	s_nop 0
	s_nop 0
	s_nop 0
	s_nop 0
	s_nop 0
	s_nop 0
	s_nop 0
	s_nop 0
	s_nop 0
	s_nop 0
	s_nop 0
	s_nop 0
	s_nop 0
	s_nop 0
	s_nop 0
	s_nop 0
	s_nop 0
	s_nop 0
	s_nop 0
	s_nop 0
	s_nop 0
	s_nop 0
	s_nop 0
	s_nop 0
	s_nop 0
	s_nop 0
	s_nop 0
	s_nop 0
	s_nop 0
	s_nop 0
	s_nop 0
	s_nop 0
	s_nop 0
	s_nop 0
	s_nop 0
	s_nop 0
	s_nop 0
	s_nop 0
	s_nop 0
	s_nop 0
	s_nop 0
	s_nop 0
	s_nop 0
	s_nop 0
	s_nop 0
	s_nop 0
	s_nop 0
	s_nop 0
	s_nop 0
	s_nop 0
	s_nop 0
	s_nop 0
	s_nop 0
	s_nop 0
	s_nop 0
	s_nop 0
	s_nop 0
	s_nop 0
	s_nop 0
	s_nop 0
	s_nop 0
	s_nop 0
	s_nop 0
	s_nop 0
	s_nop 0
	s_nop 0
	s_nop 0
	s_nop 0
	s_nop 0
	s_nop 0
	s_nop 0
	s_nop 0
	s_nop 0
	s_nop 0
	s_nop 0
	s_nop 0
	s_nop 0
	s_nop 0
	s_nop 0
	s_nop 0
	s_nop 0
	s_nop 0
	s_nop 0
	s_nop 0
	s_nop 0
	s_nop 0
	s_nop 0
	s_nop 0
	s_nop 0
	s_nop 0
	s_nop 0
	s_nop 0
	s_nop 0
	s_nop 0
	s_nop 0
	s_nop 0
	s_nop 0
	s_nop 0
	s_nop 0
	s_nop 0
	s_nop 0
	s_nop 0
	s_nop 0
	s_nop 0
	s_nop 0
	s_nop 0
	s_nop 0
	s_nop 0
	s_nop 0
	s_nop 0
	s_nop 0
	s_nop 0
	s_nop 0
	s_nop 0
	s_nop 0
	s_nop 0
	s_nop 0
	s_nop 0
	s_nop 0
	s_nop 0
	s_nop 0
	s_nop 0
	s_nop 0
	s_nop 0
	s_nop 0
	s_nop 0
	s_nop 0
	s_nop 0
	s_nop 0
	s_nop 0
	s_nop 0
	s_nop 0
	s_nop 0
	s_nop 0
	s_nop 0
	s_nop 0
	s_nop 0
	s_nop 0
	s_nop 0
	s_nop 0
	s_nop 0
	s_nop 0
	s_nop 0
	s_nop 0
	s_nop 0
	s_nop 0
	s_nop 0
	s_nop 0
	s_nop 0
	s_nop 0
	s_nop 0
	s_nop 0
	s_nop 0
	s_nop 0
	s_nop 0
	s_nop 0
	s_nop 0
	s_nop 0
	s_nop 0
	s_nop 0
	s_nop 0
	s_nop 0
	s_nop 0
	s_nop 0
	s_nop 0
	s_nop 0
	s_nop 0
	s_nop 0
	s_nop 0
	s_nop 0
	s_nop 0
	s_nop 0
	s_nop 0
	s_nop 0
	s_nop 0
	s_nop 0
	s_nop 0
	s_nop 0
	s_nop 0
	s_nop 0
	s_nop 0
	s_nop 0
	s_nop 0
	s_nop 0
	s_nop 0
	s_nop 0
	s_nop 0
	s_nop 0
	s_nop 0
	s_nop 0
	s_nop 0
	s_nop 0
	s_nop 0
	s_nop 0
	s_nop 0
	s_nop 0
	s_nop 0
	s_nop 0
	s_nop 0
	s_nop 0
	s_nop 0
	s_nop 0
	s_nop 0
	s_nop 0
	s_nop 0
	s_nop 0
	s_nop 0
	s_nop 0
	s_nop 0
	s_nop 0
	s_nop 0
	s_nop 0
	s_nop 0
	s_nop 0
	s_nop 0
	s_nop 0
	s_nop 0
	s_nop 0
	s_nop 0
	s_nop 0
	s_nop 0
	s_nop 0
	s_nop 0
	s_nop 0
	s_nop 0
	s_nop 0
	s_nop 0
	s_nop 0
	s_nop 0
	s_nop 0
	s_nop 0
	s_nop 0
	s_nop 0
	s_nop 0
	s_nop 0
	s_nop 0
	s_nop 0
	s_nop 0
	s_nop 0
	s_nop 0
	s_nop 0
	s_nop 0
	s_nop 0
	s_nop 0
	s_nop 0
	s_nop 0
	s_nop 0
	s_nop 0
	s_nop 0
	s_nop 0
	s_nop 0
	s_nop 0
	s_nop 0
	s_nop 0
	s_nop 0
	s_nop 0
	s_nop 0
	s_nop 0
	s_nop 0
	s_nop 0
	s_nop 0
	s_nop 0
	s_nop 0
	s_nop 0
	s_nop 0
	s_nop 0
	s_nop 0
	s_nop 0
	s_nop 0
	s_nop 0
	s_nop 0
	s_nop 0
	s_nop 0
	s_nop 0
	s_nop 0
	s_nop 0
	s_nop 0
	s_nop 0
	s_nop 0
	s_nop 0
	s_nop 0
	s_nop 0
	s_nop 0
	s_nop 0
	s_nop 0
	s_nop 0
	s_nop 0
	s_nop 0
	s_nop 0
	s_nop 0
	s_nop 0
	s_nop 0
	s_nop 0
	s_nop 0
	s_nop 0
	s_nop 0
	s_nop 0
	s_nop 0
	s_nop 0
	s_nop 0
	s_nop 0
	s_nop 0
	s_nop 0
	s_nop 0
	s_nop 0
	s_nop 0
	s_nop 0
	s_nop 0
	s_nop 0
	s_nop 0
	s_nop 0
	s_nop 0
	s_nop 0
	s_nop 0
	s_nop 0
	s_nop 0
	s_nop 0
	s_nop 0
	s_nop 0
	s_nop 0
	s_nop 0
	s_nop 0
	s_nop 0
	s_nop 0
	s_nop 0
	s_nop 0
	s_nop 0
	s_nop 0
	s_nop 0
	s_nop 0
	s_nop 0
	s_nop 0
	s_nop 0
	s_nop 0
	s_nop 0
	s_nop 0
	s_nop 0
	s_nop 0
	s_nop 0
	s_nop 0
	s_nop 0
	s_nop 0
	s_nop 0
	s_nop 0
	s_nop 0
	s_nop 0
	s_nop 0
	s_nop 0
	s_nop 0
	s_nop 0
	s_nop 0
	s_nop 0
	s_nop 0
	s_nop 0
	s_nop 0
	s_nop 0
.Lpagefit_4:
.LBB0_808:
	ds_read_b128 v[64:67], v149 offset:13312
	ds_read_b128 v[124:127], v149 offset:13344
	s_and_b32 s6, s61, 6
	s_cmp_lg_u32 s6, 0
	s_waitcnt lgkmcnt(1)
	v_mfma_f32_32x32x16_bf16 v[80:95], v[64:67], v[112:115], 0
	ds_read_b128 v[64:67], v149 offset:19968
	ds_read_b128 v[128:131], v149 offset:20000
	s_waitcnt lgkmcnt(1)
	v_mfma_f32_32x32x16_bf16 v[64:79], v[64:67], v[112:115], 0
	s_cbranch_scc1 .LBB0_813
	v_max3_f32 v96, v48, v49, v50
	v_max3_f32 v99, v32, v33, v34
	v_max3_f32 v98, v51, v52, v53
	v_max3_f32 v153, v35, v36, v37
	s_and_b32 s10, s61, 56
	v_max3_f32 v96, v96, v54, v55
	v_max3_f32 v99, v99, v38, v39
	v_max3_f32 v98, v98, v56, v57
	v_max3_f32 v153, v153, v40, v41
	s_cmp_eq_u32 s10, 0
	v_max3_f32 v96, v96, v58, v59
	v_max3_f32 v99, v99, v42, v43
	v_max3_f32 v98, v98, v60, v61
	v_max3_f32 v153, v153, v44, v45
	s_cselect_b64 s[6:7], -1, 0
	v_max3_f32 v96, v96, v62, v63
	v_max3_f32 v99, v99, v46, v47
	s_cmp_lg_u32 s10, 0
	v_max3_f32 v96, v96, v98, v99
	s_nop 0
	v_max_f32_e32 v96, v96, v153
	s_nop 0
	v_mov_b32_e32 v98, v96
	s_nop 1
	v_permlane32_swap_b32_e32 v96, v98
	v_max_f32_e32 v98, v98, v98
	v_max_f32_e32 v96, v96, v96
	v_max_f32_e32 v96, v96, v98
	v_cmp_lt_f32_e32 vcc, s54, v96
	v_mov_b32_e32 v98, 0
	s_cbranch_scc1 .LBB0_811
	v_cmp_gt_f32_e64 s[10:11], s55, v96
	s_cmp_lg_u64 s[10:11], 0
	s_cselect_b64 s[10:11], -1, 0
	v_cndmask_b32_e64 v98, 0, 1, s[10:11]

;     __device__ __forceinline__ void mid(f32x4 (&acc)[2][2][4][2], const Unit& u, int wr, int fr) const {
;         if constexpr (MIX) {
; #pragma unroll
;             for (int ai = 0; ai < 2; ++ai)
; #pragma unroll
;                 for (int m = 0; m < 4; ++m) { const int row = u.pm * BM + wr * 64 + fr + ai * HALF + m * 16; const f32x4 sq = *(const f32x4*)(rs2 + 4 * row); const float q = sqrtf(((sq[2] + sq[3]) * (1.f / 512.f) + NEPS) / ((sq[0] + sq[1]) * (1.f / 512.f) + NEPS));
; template <class Epi, class Sched, bool ALIGN_EPI = false, bool SP2 = false>
; __device__ __forceinline__ void gemm_phase(PG8_LAS unsigned char* lds, const Gemm g, const Sched S, const Epi E) {
;     ...
; #pragma unroll
;         for (int a = 0; a < 2; ++a)
; #pragma unroll
;             for (int b = 0; b < 2; ++b)
; #pragma unroll
;                 for (int m = 0; m < 4; ++m)
; #pragma unroll
;                     for (int n = 0; n < 2; ++n) acc[a][b][m][n] = (f32x4){0.f, 0.f, 0.f, 0.f};
;         cur = nxt; cA = nA; cB = nB; ++ui;
.LBB0_897:
	s_ashr_i32 s51, s50, 31
	s_lshl_b64 s[10:11], s[50:51], 19
	s_add_u32 s52, s48, s10
	v_lshl_add_u32 v2, s64, 10, v171
	s_addc_u32 s53, s49, s11
	v_add_u32_e32 v4, 0x200, v2
	s_and_b64 s[10:11], s[0:1], exec
	v_ashrrev_i32_e32 v5, 31, v4
	s_cselect_b32 s51, s53, s67
	s_cselect_b32 s72, s52, s66
	s_ashr_i32 s45, s44, 31
	v_lshl_add_u64 v[130:131], v[4:5], 2, s[46:47]
	v_add_u32_e32 v4, 0x240, v2
	s_lshl_b64 s[10:11], s[44:45], 19
	v_readlane_b32 s14, v255, 34
	v_ashrrev_i32_e32 v3, 31, v2
	v_ashrrev_i32_e32 v5, 31, v4
	v_readlane_b32 s15, v255, 35
	s_add_u32 s62, s14, s10
	v_lshl_add_u64 v[128:129], v[2:3], 2, s[46:47]
	v_lshl_add_u64 v[132:133], v[4:5], 2, s[46:47]
	v_add_u32_e32 v4, 0x280, v2
	v_add_u32_e32 v2, 0x2c0, v2
	s_addc_u32 s63, s15, s11
	v_ashrrev_i32_e32 v3, 31, v2
	s_and_b64 s[10:11], s[0:1], exec
	v_ashrrev_i32_e32 v5, 31, v4
	v_lshl_add_u64 v[136:137], v[2:3], 2, s[46:47]
	v_mov_b32_e32 v2, v0
	v_mov_b32_e32 v3, v0
	s_cselect_b32 s45, s63, s7
	s_cselect_b32 s73, s62, s6
	v_lshl_add_u64 v[134:135], v[4:5], 2, s[46:47]
	s_add_u32 s74, s6, 0x100
	v_mov_b32_e32 v1, v0
	v_mov_b64_e32 v[6:7], v[2:3]
	v_mov_b64_e32 v[10:11], v[2:3]
	v_mov_b64_e32 v[22:23], v[2:3]
	v_mov_b64_e32 v[26:27], v[2:3]
	v_mov_b64_e32 v[38:39], v[2:3]
	v_mov_b64_e32 v[42:43], v[2:3]
	v_mov_b64_e32 v[54:55], v[2:3]
	v_mov_b64_e32 v[58:59], v[2:3]
	v_mov_b64_e32 v[14:15], v[2:3]
	v_mov_b64_e32 v[18:19], v[2:3]
	v_mov_b64_e32 v[30:31], v[2:3]
	v_mov_b64_e32 v[34:35], v[2:3]
	v_mov_b64_e32 v[46:47], v[2:3]
	v_mov_b64_e32 v[50:51], v[2:3]
	v_mov_b64_e32 v[62:63], v[2:3]
	v_mov_b64_e32 v[66:67], v[2:3]
	v_mov_b64_e32 v[70:71], v[2:3]
	v_mov_b64_e32 v[74:75], v[2:3]
	v_mov_b64_e32 v[86:87], v[2:3]
	v_mov_b64_e32 v[90:91], v[2:3]
	v_mov_b64_e32 v[102:103], v[2:3]
	v_mov_b64_e32 v[106:107], v[2:3]
	v_mov_b64_e32 v[118:119], v[2:3]
	v_mov_b64_e32 v[126:127], v[2:3]
	v_mov_b64_e32 v[78:79], v[2:3]
	v_mov_b64_e32 v[82:83], v[2:3]
	v_mov_b64_e32 v[94:95], v[2:3]
	v_mov_b64_e32 v[98:99], v[2:3]
	v_mov_b64_e32 v[110:111], v[2:3]
	v_mov_b64_e32 v[114:115], v[2:3]
	v_mov_b64_e32 v[142:143], v[2:3]
	v_mov_b64_e32 v[146:147], v[2:3]
	v_lshl_add_u64 v[138:139], s[66:67], 0, v[156:157]
	v_lshl_add_u64 v[164:165], s[66:67], 0, v[158:159]
	s_addc_u32 s75, s7, 0
	s_mov_b32 s76, -2
	s_mov_b64 s[70:71], 0
	v_mov_b64_e32 v[4:5], v[0:1]
	v_mov_b64_e32 v[8:9], v[0:1]
	v_mov_b64_e32 v[20:21], v[0:1]
	v_mov_b64_e32 v[24:25], v[0:1]
	v_mov_b64_e32 v[36:37], v[0:1]
	v_mov_b64_e32 v[40:41], v[0:1]
	v_mov_b64_e32 v[52:53], v[0:1]
	v_mov_b64_e32 v[56:57], v[0:1]
	v_mov_b64_e32 v[12:13], v[0:1]
	v_mov_b64_e32 v[16:17], v[0:1]
	v_mov_b64_e32 v[28:29], v[0:1]
	v_mov_b64_e32 v[32:33], v[0:1]
	v_mov_b64_e32 v[44:45], v[0:1]
	v_mov_b64_e32 v[48:49], v[0:1]
	v_mov_b64_e32 v[60:61], v[0:1]
	v_mov_b64_e32 v[64:65], v[0:1]
	v_mov_b64_e32 v[68:69], v[0:1]
	v_mov_b64_e32 v[72:73], v[0:1]
	v_mov_b64_e32 v[84:85], v[0:1]
	v_mov_b64_e32 v[88:89], v[0:1]
	v_mov_b64_e32 v[100:101], v[0:1]
	v_mov_b64_e32 v[104:105], v[0:1]
	v_mov_b64_e32 v[116:117], v[0:1]
	v_mov_b64_e32 v[124:125], v[0:1]
	v_mov_b64_e32 v[76:77], v[0:1]
	v_mov_b64_e32 v[80:81], v[0:1]
	v_mov_b64_e32 v[92:93], v[0:1]
	v_mov_b64_e32 v[96:97], v[0:1]
	v_mov_b64_e32 v[108:109], v[0:1]
	v_mov_b64_e32 v[112:113], v[0:1]
	v_mov_b64_e32 v[140:141], v[0:1]
	v_mov_b64_e32 v[144:145], v[0:1]
	s_branch .LBB0_899
	s_branch .Lpagefit_5
	s_nop 0
	s_nop 0
	s_nop 0
	s_nop 0
	s_nop 0
	s_nop 0
	s_nop 0
	s_nop 0
	s_nop 0
	s_nop 0
	s_nop 0
	s_nop 0
	s_nop 0
	s_nop 0
	s_nop 0
	s_nop 0
	s_nop 0
	s_nop 0
	s_nop 0
	s_nop 0
	s_nop 0
	s_nop 0
	s_nop 0
	s_nop 0
	s_nop 0
	s_nop 0
	s_nop 0
	s_nop 0
	s_nop 0
	s_nop 0
	s_nop 0
	s_nop 0
	s_nop 0
	s_nop 0
	s_nop 0
	s_nop 0
	s_nop 0
	s_nop 0
	s_nop 0
	s_nop 0
	s_nop 0
	s_nop 0
	s_nop 0
	s_nop 0
	s_nop 0
	s_nop 0
	s_nop 0
	s_nop 0
	s_nop 0
	s_nop 0
	s_nop 0
	s_nop 0
	s_nop 0
	s_nop 0
	s_nop 0
	s_nop 0
	s_nop 0
	s_nop 0
	s_nop 0
	s_nop 0
	s_nop 0
	s_nop 0
	s_nop 0
	s_nop 0
	s_nop 0
	s_nop 0
	s_nop 0
	s_nop 0
	s_nop 0
	s_nop 0
	s_nop 0
	s_nop 0
	s_nop 0
	s_nop 0
	s_nop 0
	s_nop 0
	s_nop 0
	s_nop 0
	s_nop 0
	s_nop 0
	s_nop 0
	s_nop 0
	s_nop 0
	s_nop 0
	s_nop 0
	s_nop 0
	s_nop 0
	s_nop 0
	s_nop 0
	s_nop 0
	s_nop 0
	s_nop 0
	s_nop 0
	s_nop 0
	s_nop 0
	s_nop 0
	s_nop 0
	s_nop 0
	s_nop 0
	s_nop 0
	s_nop 0
	s_nop 0
	s_nop 0
	s_nop 0
	s_nop 0
	s_nop 0
	s_nop 0
	s_nop 0
	s_nop 0
	s_nop 0
	s_nop 0
	s_nop 0
	s_nop 0
	s_nop 0
	s_nop 0
	s_nop 0
	s_nop 0
	s_nop 0
	s_nop 0
	s_nop 0
	s_nop 0
	s_nop 0
	s_nop 0
	s_nop 0
	s_nop 0
	s_nop 0
	s_nop 0
	s_nop 0
	s_nop 0
	s_nop 0
	s_nop 0
	s_nop 0
	s_nop 0
	s_nop 0
	s_nop 0
	s_nop 0
	s_nop 0
	s_nop 0
	s_nop 0
	s_nop 0
	s_nop 0
	s_nop 0
	s_nop 0
	s_nop 0
	s_nop 0
	s_nop 0
	s_nop 0
	s_nop 0
	s_nop 0
	s_nop 0
	s_nop 0
	s_nop 0
	s_nop 0
	s_nop 0
	s_nop 0
	s_nop 0
	s_nop 0
	s_nop 0
	s_nop 0
	s_nop 0
	s_nop 0
	s_nop 0
	s_nop 0
	s_nop 0
	s_nop 0
	s_nop 0
	s_nop 0
	s_nop 0
	s_nop 0
	s_nop 0
	s_nop 0
	s_nop 0
	s_nop 0
	s_nop 0
	s_nop 0
	s_nop 0
	s_nop 0
	s_nop 0
	s_nop 0
	s_nop 0
	s_nop 0
	s_nop 0
	s_nop 0
	s_nop 0
	s_nop 0
	s_nop 0
	s_nop 0
	s_nop 0
	s_nop 0
	s_nop 0
	s_nop 0
	s_nop 0
	s_nop 0
	s_nop 0
	s_nop 0
	s_nop 0
	s_nop 0
	s_nop 0
	s_nop 0
	s_nop 0
	s_nop 0
	s_nop 0
	s_nop 0
	s_nop 0
	s_nop 0
	s_nop 0
	s_nop 0
	s_nop 0
	s_nop 0
	s_nop 0
	s_nop 0
	s_nop 0
	s_nop 0
	s_nop 0
	s_nop 0
	s_nop 0
	s_nop 0
	s_nop 0
	s_nop 0
	s_nop 0
	s_nop 0
	s_nop 0
	s_nop 0
	s_nop 0
	s_nop 0
	s_nop 0
	s_nop 0
	s_nop 0
	s_nop 0
	s_nop 0
	s_nop 0
	s_nop 0
	s_nop 0
	s_nop 0
	s_nop 0
	s_nop 0
	s_nop 0
	s_nop 0
	s_nop 0
	s_nop 0
	s_nop 0
	s_nop 0
	s_nop 0
	s_nop 0
	s_nop 0
	s_nop 0
	s_nop 0
	s_nop 0
	s_nop 0
	s_nop 0
; #define PG8_STAGE(bufoff, gbase, voff) do { _Pragma("unroll") for (int _i = 0; _i < 2; ++_i) \
;         __builtin_amdgcn_global_load_lds((const unsigned*)((const char*)(gbase) + (voff)[_i]), (PG8_LAS unsigned*)(lds + (bufoff) + ldsw + _i * 8192), 16, 0, 0); } while (0)
; #define PG8_LDA(dst, b, h) do { _Pragma("unroll") for (int m = 0; m < 4; ++m) _Pragma("unroll") for (int k = 0; k < 2; ++k) dst[m][k] = *(const PG8_LAS bf16x8*)(lds + PG8_SA(b, h) + aoff + m * 2048 + k * 1024); } while (0)
; #define PG8_LDB(dst, b, h) do { _Pragma("unroll") for (int n = 0; n < 2; ++n) _Pragma("unroll") for (int k = 0; k < 2; ++k) dst[n][k] = *(const PG8_LAS bf16x8*)(lds + PG8_SB(b, h) + boff + n * 2048 + k * 1024); } while (0)
; #define PG8_MMA(ai, bj, At, Bt) do { __builtin_amdgcn_s_setprio(1); _Pragma("unroll") for (int m = 0; m < 4; ++m) _Pragma("unroll") for (int n = 0; n < 2; ++n) _Pragma("unroll") for (int k = 0; k < 2; ++k) \
;         acc[ai][bj][m][n] = __builtin_amdgcn_mfma_f32_16x16x32_bf16(Bt[n][k], At[m][k], acc[ai][bj][m][n], 0, 0, 0); __builtin_amdgcn_s_setprio(0); } while (0)
; #define PG8_WAIT_V(n) asm volatile("s_waitcnt vmcnt(" #n ")" ::: "memory")
; #define PG8_WAIT_L(n) asm volatile("s_waitcnt lgkmcnt(" #n ")" ::: "memory")
; #define PG8_BAR __builtin_amdgcn_s_barrier()
; #define PG8_SCHED __builtin_amdgcn_sched_barrier(0)
; template <class Epi, class Sched, bool ALIGN_EPI = false, bool SP2 = false>
; __device__ __forceinline__ void gemm_phase(PG8_LAS unsigned char* lds, const Gemm g, const Sched S, const Epi E) {
;     ...
;             if constexpr (SP2) {
;             PG8_LDB(B0, 0, 0); PG8_LDB(B1, 0, 1); PG8_SCHED; PG8_LDA(At, 0, 0); PG8_STAGE(PG8_SA(1, 1), a1 + hstep, voffA);
;             PG8_WAIT_V(8); PG8_WAIT_L(0); PG8_BAR; PG8_MMA(0, 0, At, B0); PG8_MMA(0, 1, At, B1); PG8_BAR; PG8_SCHED;
	s_nop 0
	s_nop 0
	s_nop 0
	s_nop 0
	s_nop 0
	s_nop 0
	s_nop 0
	s_nop 0
	s_nop 0
	s_nop 0
	s_nop 0
	s_nop 0
	s_nop 0
	s_nop 0
	s_nop 0
	s_nop 0
	s_nop 0
	s_nop 0
	s_nop 0
	s_nop 0
	s_nop 0
	s_nop 0
	s_nop 0
	s_nop 0
	s_nop 0
	s_nop 0
	s_nop 0
	s_nop 0
	s_nop 0
	s_nop 0
	s_nop 0
	s_nop 0
	s_nop 0
	s_nop 0
	s_nop 0
	s_nop 0
	s_nop 0
	s_nop 0
	s_nop 0
	s_nop 0
	s_nop 0
	s_nop 0
	s_nop 0
	s_nop 0
	s_nop 0
	s_nop 0
	s_nop 0
	s_nop 0
	s_nop 0
	s_nop 0
	s_nop 0
	s_nop 0
	s_nop 0
	s_nop 0
	s_nop 0
	s_nop 0
	s_nop 0
	s_nop 0
	s_nop 0
	s_nop 0
	s_nop 0
	s_nop 0
	s_nop 0
	s_nop 0
	s_nop 0
	s_nop 0
	s_nop 0
	s_nop 0
	s_nop 0
	s_nop 0
	s_nop 0
	s_nop 0
	s_nop 0
	s_nop 0
	s_nop 0
	s_nop 0
	s_nop 0
	s_nop 0
	s_nop 0
	s_nop 0
	s_nop 0
	s_nop 0
	s_nop 0
	s_nop 0
	s_nop 0
	s_nop 0
	s_nop 0
	s_nop 0
	s_nop 0
	s_nop 0
	s_nop 0
	s_nop 0
	s_nop 0
	s_nop 0
	s_nop 0
	s_nop 0
	s_nop 0
	s_nop 0
	s_nop 0
	s_nop 0
	s_nop 0
	s_nop 0
	s_nop 0
	s_nop 0
	s_nop 0
	s_nop 0
	s_nop 0
	s_nop 0
	s_nop 0
	s_nop 0
	s_nop 0
	s_nop 0
	s_nop 0
	s_nop 0
	s_nop 0
	s_nop 0
	s_nop 0
	s_nop 0
	s_nop 0
	s_nop 0
	s_nop 0
	s_nop 0
	s_nop 0
	s_nop 0
	s_nop 0
	s_nop 0
	s_nop 0
	s_nop 0
	s_nop 0
	s_nop 0
	s_nop 0
	s_nop 0
	s_nop 0
	s_nop 0
	s_nop 0
	s_nop 0
	s_nop 0
	s_nop 0
	s_nop 0
	s_nop 0
	s_nop 0
	s_nop 0
	s_nop 0
	s_nop 0
	s_nop 0
	s_nop 0
	s_nop 0
	s_nop 0
	s_nop 0
	s_nop 0
	s_nop 0
	s_nop 0
	s_nop 0
	s_nop 0
	s_nop 0
	s_nop 0
	s_nop 0
	s_nop 0
	s_nop 0
	s_nop 0
	s_nop 0
	s_nop 0
	s_nop 0
	s_nop 0
	s_nop 0
	s_nop 0
	s_nop 0
	s_nop 0
	s_nop 0
	s_nop 0
	s_nop 0
	s_nop 0
	s_nop 0
	s_nop 0
	s_nop 0
	s_nop 0
	s_nop 0
	s_nop 0
	s_nop 0
	s_nop 0
	s_nop 0
	s_nop 0
	s_nop 0
	s_nop 0
	s_nop 0
	s_nop 0
	s_nop 0
	s_nop 0
	s_nop 0
	s_nop 0
	s_nop 0
	s_nop 0
	s_nop 0
	s_nop 0
	s_nop 0
	s_nop 0
	s_nop 0
	s_nop 0
	s_nop 0
	s_nop 0
	s_nop 0
	s_nop 0
	s_nop 0
	s_nop 0
	s_nop 0
	s_nop 0
	s_nop 0
	s_nop 0
	s_nop 0
	s_nop 0
	s_nop 0
	s_nop 0
	s_nop 0
	s_nop 0
	s_nop 0
	s_nop 0
	s_nop 0
	s_nop 0
	s_nop 0
	s_nop 0
	s_nop 0
	s_nop 0
	s_nop 0
	s_nop 0
	s_nop 0
	s_nop 0
	s_nop 0
	s_nop 0
	s_nop 0
	s_nop 0
	s_nop 0
	s_nop 0
	s_nop 0
	s_nop 0
	s_nop 0
	s_nop 0
	s_nop 0
	s_nop 0
	s_nop 0
	s_nop 0
	s_nop 0
	s_nop 0
	s_nop 0
	s_nop 0
	s_nop 0
	s_nop 0
	s_nop 0
	s_nop 0
	s_nop 0
	s_nop 0
	s_nop 0
	s_nop 0
	s_nop 0
	s_nop 0
	s_nop 0
	s_nop 0
	s_nop 0
	s_nop 0
	s_nop 0
	s_nop 0
	s_nop 0
	s_nop 0
	s_nop 0
	s_nop 0
	s_nop 0
	s_nop 0
	s_nop 0
	s_nop 0
	s_nop 0
	s_nop 0
	s_nop 0
	s_nop 0
	s_nop 0
	s_nop 0
	s_nop 0
	s_nop 0
	s_nop 0
	s_nop 0
	s_nop 0
	s_nop 0
	s_nop 0
	s_nop 0
	s_nop 0
	s_nop 0
	s_nop 0
	s_nop 0
	s_nop 0
	s_nop 0
	s_nop 0
	s_nop 0
	s_nop 0
	s_nop 0
	s_nop 0
	s_nop 0
	s_nop 0
	s_nop 0
	s_nop 0
	s_nop 0
	s_nop 0
	s_nop 0
	s_nop 0
	s_nop 0
	s_nop 0
	s_nop 0
	s_nop 0
	s_nop 0
	s_nop 0
	s_nop 0
	s_nop 0
	s_nop 0
.Lpagefit_5:
.LBB0_898:
	v_add_u32_e32 v1, s65, v170
	ds_read_b128 v[120:123], v1
	ds_read_b128 v[176:179], v1 offset:1024
	ds_read_b128 v[180:183], v1 offset:2048
	ds_read_b128 v[190:193], v1 offset:3072
	v_add_u32_e32 v1, s68, v170
	s_add_u32 s6, s66, s70
	ds_read_b128 v[194:197], v1
	ds_read_b128 v[198:201], v1 offset:1024
	ds_read_b128 v[202:205], v1 offset:2048
	ds_read_b128 v[206:209], v1 offset:3072
	s_addc_u32 s7, s67, s71
	s_add_u32 s6, s6, 0x100
	s_addc_u32 s7, s7, 0
	s_add_u32 s14, s74, s70
	s_addc_u32 s15, s75, s71
	s_cmpk_eq_i32 s70, 0x700
	s_cselect_b32 s11, s51, s7
	s_cselect_b32 s10, s72, s6
	s_cselect_b32 s7, s45, s15
	s_cselect_b32 s6, s73, s14
	v_lshl_add_u64 v[2:3], v[138:139], 0, s[70:71]
	s_add_i32 m0, s9, 0xc000
	ds_read_b128 v[210:213], v173
	ds_read_b128 v[214:217], v173 offset:1024
	ds_read_b128 v[218:221], v173 offset:2048
	ds_read_b128 v[222:225], v173 offset:3072
	ds_read_b128 v[226:229], v173 offset:4096
	ds_read_b128 v[230:233], v173 offset:5120
	ds_read_b128 v[234:237], v173 offset:6144
	ds_read_b128 v[238:241], v173 offset:7168
	global_load_lds_dwordx4 v[2:3], off
	v_lshl_add_u64 v[2:3], v[164:165], 0, s[70:71]
	s_add_i32 m0, s9, 0xe000
	s_nop 0
	global_load_lds_dwordx4 v[2:3], off
	s_waitcnt vmcnt(8)
	s_waitcnt lgkmcnt(0)
	s_barrier
	s_setprio 1
	s_waitcnt lgkmcnt(0)
	v_mfma_f32_16x16x32_bf16 v[144:147], v[120:123], v[210:213], v[144:147]
	v_mfma_f32_16x16x32_bf16 v[140:143], v[180:183], v[210:213], v[140:143]
	v_mfma_f32_16x16x32_bf16 v[112:115], v[120:123], v[218:221], v[112:115]
	v_mfma_f32_16x16x32_bf16 v[108:111], v[180:183], v[218:221], v[108:111]
	v_mfma_f32_16x16x32_bf16 v[96:99], v[120:123], v[226:229], v[96:99]
	v_mfma_f32_16x16x32_bf16 v[92:95], v[180:183], v[226:229], v[92:95]
	v_mfma_f32_16x16x32_bf16 v[80:83], v[120:123], v[234:237], v[80:83]
	v_mfma_f32_16x16x32_bf16 v[76:79], v[180:183], v[234:237], v[76:79]
	v_mfma_f32_16x16x32_bf16 v[144:147], v[176:179], v[214:217], v[144:147]
	v_mfma_f32_16x16x32_bf16 v[140:143], v[190:193], v[214:217], v[140:143]
	v_mfma_f32_16x16x32_bf16 v[112:115], v[176:179], v[222:225], v[112:115]
	v_mfma_f32_16x16x32_bf16 v[108:111], v[190:193], v[222:225], v[108:111]
	v_mfma_f32_16x16x32_bf16 v[96:99], v[176:179], v[230:233], v[96:99]
	v_mfma_f32_16x16x32_bf16 v[92:95], v[190:193], v[230:233], v[92:95]
	v_mfma_f32_16x16x32_bf16 v[80:83], v[176:179], v[238:241], v[80:83]
	v_mfma_f32_16x16x32_bf16 v[76:79], v[190:193], v[238:241], v[76:79]
	s_setprio 0
	s_setprio 1
	v_mfma_f32_16x16x32_bf16 v[124:127], v[194:197], v[210:213], v[124:127]
	v_mfma_f32_16x16x32_bf16 v[116:119], v[202:205], v[210:213], v[116:119]
	v_mfma_f32_16x16x32_bf16 v[104:107], v[194:197], v[218:221], v[104:107]
	v_mfma_f32_16x16x32_bf16 v[100:103], v[202:205], v[218:221], v[100:103]
	v_mfma_f32_16x16x32_bf16 v[88:91], v[194:197], v[226:229], v[88:91]
	v_mfma_f32_16x16x32_bf16 v[84:87], v[202:205], v[226:229], v[84:87]
	v_mfma_f32_16x16x32_bf16 v[72:75], v[194:197], v[234:237], v[72:75]
	v_mfma_f32_16x16x32_bf16 v[68:71], v[202:205], v[234:237], v[68:71]
	v_mfma_f32_16x16x32_bf16 v[124:127], v[198:201], v[214:217], v[124:127]
	v_mfma_f32_16x16x32_bf16 v[116:119], v[206:209], v[214:217], v[116:119]
	v_mfma_f32_16x16x32_bf16 v[104:107], v[198:201], v[222:225], v[104:107]
	v_mfma_f32_16x16x32_bf16 v[100:103], v[206:209], v[222:225], v[100:103]
	v_mfma_f32_16x16x32_bf16 v[88:91], v[198:201], v[230:233], v[88:91]
	v_mfma_f32_16x16x32_bf16 v[84:87], v[206:209], v[230:233], v[84:87]
	v_mfma_f32_16x16x32_bf16 v[72:75], v[198:201], v[238:241], v[72:75]
	v_mfma_f32_16x16x32_bf16 v[68:71], v[206:209], v[238:241], v[68:71]
	s_setprio 0
	s_barrier
; #define PG8_STAGE(bufoff, gbase, voff) do { _Pragma("unroll") for (int _i = 0; _i < 2; ++_i) \
;         __builtin_amdgcn_global_load_lds((const unsigned*)((const char*)(gbase) + (voff)[_i]), (PG8_LAS unsigned*)(lds + (bufoff) + ldsw + _i * 8192), 16, 0, 0); } while (0)
; #define PG8_LDA(dst, b, h) do { _Pragma("unroll") for (int m = 0; m < 4; ++m) _Pragma("unroll") for (int k = 0; k < 2; ++k) dst[m][k] = *(const PG8_LAS bf16x8*)(lds + PG8_SA(b, h) + aoff + m * 2048 + k * 1024); } while (0)
; #define PG8_LDB(dst, b, h) do { _Pragma("unroll") for (int n = 0; n < 2; ++n) _Pragma("unroll") for (int k = 0; k < 2; ++k) dst[n][k] = *(const PG8_LAS bf16x8*)(lds + PG8_SB(b, h) + boff + n * 2048 + k * 1024); } while (0)
; #define PG8_MMA(ai, bj, At, Bt) do { __builtin_amdgcn_s_setprio(1); _Pragma("unroll") for (int m = 0; m < 4; ++m) _Pragma("unroll") for (int n = 0; n < 2; ++n) _Pragma("unroll") for (int k = 0; k < 2; ++k) \
;         acc[ai][bj][m][n] = __builtin_amdgcn_mfma_f32_16x16x32_bf16(Bt[n][k], At[m][k], acc[ai][bj][m][n], 0, 0, 0); __builtin_amdgcn_s_setprio(0); } while (0)
; #define PG8_WAIT_V(n) asm volatile("s_waitcnt vmcnt(" #n ")" ::: "memory")
; #define PG8_WAIT_L(n) asm volatile("s_waitcnt lgkmcnt(" #n ")" ::: "memory")
; #define PG8_BAR __builtin_amdgcn_s_barrier()
; #define PG8_SCHED __builtin_amdgcn_sched_barrier(0)
; template <class Epi, class Sched, bool ALIGN_EPI = false, bool SP2 = false>
; __device__ __forceinline__ void gemm_phase(PG8_LAS unsigned char* lds, const Gemm g, const Sched S, const Epi E) {
;     ...
;             PG8_LDA(At, 0, 1); PG8_STAGE(PG8_SB(0, 0), b2, voffB); PG8_STAGE(PG8_SB(0, 1), b2 + hstep, voffB); PG8_STAGE(PG8_SA(0, 0), a2, voffA);
;             PG8_WAIT_V(8); PG8_WAIT_L(0); PG8_BAR; PG8_MMA(1, 0, At, B0); PG8_MMA(1, 1, At, B1); PG8_BAR; PG8_SCHED;
;             PG8_LDB(B0, 1, 0); PG8_LDB(B1, 1, 1); PG8_SCHED; PG8_LDA(At, 1, 0); PG8_STAGE(PG8_SA(0, 1), a2 + hstep, voffA);
;             PG8_WAIT_V(8); PG8_WAIT_L(0); PG8_BAR; PG8_MMA(0, 0, At, B0); PG8_MMA(0, 1, At, B1); PG8_BAR; PG8_SCHED;
	s_add_i32 s14, s65, s8
	v_lshl_add_u64 v[166:167], s[6:7], 0, v[150:151]
	s_mov_b32 m0, s14
	ds_read_b128 v[210:213], v173 offset:16384
	ds_read_b128 v[214:217], v173 offset:17408
	ds_read_b128 v[218:221], v173 offset:18432
	ds_read_b128 v[222:225], v173 offset:19456
	ds_read_b128 v[226:229], v173 offset:20480
	ds_read_b128 v[230:233], v173 offset:21504
	ds_read_b128 v[234:237], v173 offset:22528
	ds_read_b128 v[238:241], v173 offset:23552
	global_load_lds_dwordx4 v[166:167], off
	s_add_i32 m0, s14, 0x2000
	s_add_u32 s14, s6, 0x40000
	v_lshl_add_u64 v[184:185], s[6:7], 0, v[154:155]
	s_addc_u32 s15, s7, 0
	s_add_i32 s77, s68, s8
	global_load_lds_dwordx4 v[184:185], off
	v_lshl_add_u64 v[2:3], s[14:15], 0, v[150:151]
	s_mov_b32 m0, s77
	v_lshl_add_u64 v[186:187], s[10:11], 0, v[148:149]
	global_load_lds_dwordx4 v[2:3], off
	v_lshl_add_u64 v[2:3], s[14:15], 0, v[154:155]
	s_add_i32 m0, s77, 0x2000
	v_lshl_add_u64 v[242:243], s[10:11], 0, v[152:153]
	global_load_lds_dwordx4 v[2:3], off
	s_mov_b32 m0, s9
	s_nop 0
	global_load_lds_dwordx4 v[186:187], off
	s_mov_b32 m0, s12
	s_nop 0
	global_load_lds_dwordx4 v[242:243], off
	s_waitcnt vmcnt(8)
	s_waitcnt lgkmcnt(0)
	s_barrier
	s_setprio 1
	s_waitcnt lgkmcnt(0)
	v_mfma_f32_16x16x32_bf16 v[64:67], v[120:123], v[210:213], v[64:67]
	v_mfma_f32_16x16x32_bf16 v[60:63], v[180:183], v[210:213], v[60:63]
	v_mfma_f32_16x16x32_bf16 v[48:51], v[120:123], v[218:221], v[48:51]
	v_mfma_f32_16x16x32_bf16 v[44:47], v[180:183], v[218:221], v[44:47]
	v_mfma_f32_16x16x32_bf16 v[32:35], v[120:123], v[226:229], v[32:35]
	v_mfma_f32_16x16x32_bf16 v[28:31], v[180:183], v[226:229], v[28:31]
	v_mfma_f32_16x16x32_bf16 v[16:19], v[120:123], v[234:237], v[16:19]
	v_mfma_f32_16x16x32_bf16 v[12:15], v[180:183], v[234:237], v[12:15]
	v_mfma_f32_16x16x32_bf16 v[64:67], v[176:179], v[214:217], v[64:67]
	v_mfma_f32_16x16x32_bf16 v[60:63], v[190:193], v[214:217], v[60:63]
	v_mfma_f32_16x16x32_bf16 v[48:51], v[176:179], v[222:225], v[48:51]
	v_mfma_f32_16x16x32_bf16 v[44:47], v[190:193], v[222:225], v[44:47]
	v_mfma_f32_16x16x32_bf16 v[32:35], v[176:179], v[230:233], v[32:35]
	v_mfma_f32_16x16x32_bf16 v[28:31], v[190:193], v[230:233], v[28:31]
	v_mfma_f32_16x16x32_bf16 v[16:19], v[176:179], v[238:241], v[16:19]
	v_mfma_f32_16x16x32_bf16 v[12:15], v[190:193], v[238:241], v[12:15]
	s_setprio 0
	s_setprio 1
	v_mfma_f32_16x16x32_bf16 v[56:59], v[194:197], v[210:213], v[56:59]
	v_mfma_f32_16x16x32_bf16 v[52:55], v[202:205], v[210:213], v[52:55]
	v_mfma_f32_16x16x32_bf16 v[40:43], v[194:197], v[218:221], v[40:43]
	v_mfma_f32_16x16x32_bf16 v[36:39], v[202:205], v[218:221], v[36:39]
	v_mfma_f32_16x16x32_bf16 v[24:27], v[194:197], v[226:229], v[24:27]
	v_mfma_f32_16x16x32_bf16 v[20:23], v[202:205], v[226:229], v[20:23]
	v_mfma_f32_16x16x32_bf16 v[8:11], v[194:197], v[234:237], v[8:11]
	v_mfma_f32_16x16x32_bf16 v[2:5], v[202:205], v[234:237], v[4:7]
	v_mfma_f32_16x16x32_bf16 v[56:59], v[198:201], v[214:217], v[56:59]
	v_mfma_f32_16x16x32_bf16 v[52:55], v[206:209], v[214:217], v[52:55]
	v_mfma_f32_16x16x32_bf16 v[40:43], v[198:201], v[222:225], v[40:43]
	v_mfma_f32_16x16x32_bf16 v[36:39], v[206:209], v[222:225], v[36:39]
	v_mfma_f32_16x16x32_bf16 v[24:27], v[198:201], v[230:233], v[24:27]
	v_mfma_f32_16x16x32_bf16 v[20:23], v[206:209], v[230:233], v[20:23]
	v_mfma_f32_16x16x32_bf16 v[8:11], v[198:201], v[238:241], v[8:11]
	v_mfma_f32_16x16x32_bf16 v[2:5], v[206:209], v[238:241], v[2:5]
	s_setprio 0
	s_barrier
	s_add_i32 s14, 0, 0x18000
	v_add_u32_e32 v1, s14, v170
	s_add_i32 s15, 0, 0x1c000
	ds_read_b128 v[120:123], v1
	ds_read_b128 v[176:179], v1 offset:1024
	ds_read_b128 v[180:183], v1 offset:2048
	ds_read_b128 v[190:193], v1 offset:3072
	v_add_u32_e32 v1, s15, v170
	ds_read_b128 v[194:197], v1
	ds_read_b128 v[198:201], v1 offset:1024
	ds_read_b128 v[202:205], v1 offset:2048
	ds_read_b128 v[206:209], v1 offset:3072
	s_add_u32 s10, s10, 0x40000
	s_addc_u32 s11, s11, 0
	s_mov_b32 m0, s13
	v_lshl_add_u64 v[6:7], s[10:11], 0, v[148:149]
	ds_read_b128 v[210:213], v173 offset:32768
	ds_read_b128 v[214:217], v173 offset:33792
	ds_read_b128 v[218:221], v173 offset:34816
	ds_read_b128 v[222:225], v173 offset:35840
	ds_read_b128 v[226:229], v173 offset:36864
	ds_read_b128 v[230:233], v173 offset:37888
	ds_read_b128 v[234:237], v173 offset:38912
	ds_read_b128 v[238:241], v173 offset:39936
	global_load_lds_dwordx4 v[6:7], off
	v_lshl_add_u64 v[6:7], s[10:11], 0, v[152:153]
	s_mov_b32 m0, s33
	s_nop 0
	global_load_lds_dwordx4 v[6:7], off
	s_waitcnt vmcnt(8)
	s_waitcnt lgkmcnt(0)
	s_barrier
; #define PG8_STAGE(bufoff, gbase, voff) do { _Pragma("unroll") for (int _i = 0; _i < 2; ++_i) \
;         __builtin_amdgcn_global_load_lds((const unsigned*)((const char*)(gbase) + (voff)[_i]), (PG8_LAS unsigned*)(lds + (bufoff) + ldsw + _i * 8192), 16, 0, 0); } while (0)
; #define PG8_LDA(dst, b, h) do { _Pragma("unroll") for (int m = 0; m < 4; ++m) _Pragma("unroll") for (int k = 0; k < 2; ++k) dst[m][k] = *(const PG8_LAS bf16x8*)(lds + PG8_SA(b, h) + aoff + m * 2048 + k * 1024); } while (0)
; #define PG8_MMA(ai, bj, At, Bt) do { __builtin_amdgcn_s_setprio(1); _Pragma("unroll") for (int m = 0; m < 4; ++m) _Pragma("unroll") for (int n = 0; n < 2; ++n) _Pragma("unroll") for (int k = 0; k < 2; ++k) \
;         acc[ai][bj][m][n] = __builtin_amdgcn_mfma_f32_16x16x32_bf16(Bt[n][k], At[m][k], acc[ai][bj][m][n], 0, 0, 0); __builtin_amdgcn_s_setprio(0); } while (0)
; #define PG8_WAIT_V(n) asm volatile("s_waitcnt vmcnt(" #n ")" ::: "memory")
; #define PG8_WAIT_L(n) asm volatile("s_waitcnt lgkmcnt(" #n ")" ::: "memory")
; #define PG8_BAR __builtin_amdgcn_s_barrier()
; #define PG8_SCHED __builtin_amdgcn_sched_barrier(0)
; template <class Epi, class Sched, bool ALIGN_EPI = false, bool SP2 = false>
; __device__ __forceinline__ void gemm_phase(PG8_LAS unsigned char* lds, const Gemm g, const Sched S, const Epi E) {
;     ...
;             PG8_WAIT_V(8); PG8_WAIT_L(0); PG8_BAR; PG8_MMA(0, 0, At, B0); PG8_MMA(0, 1, At, B1); PG8_BAR; PG8_SCHED;
;             PG8_LDA(At, 1, 1); PG8_STAGE(PG8_SB(1, 0), b3, voffB); PG8_STAGE(PG8_SB(1, 1), b3 + hstep, voffB); PG8_STAGE(PG8_SA(1, 0), a3, voffA);
;             PG8_WAIT_V(8); PG8_WAIT_L(0); PG8_BAR; PG8_MMA(1, 0, At, B0); PG8_MMA(1, 1, At, B1); PG8_BAR; PG8_SCHED;
	s_setprio 1
	s_waitcnt lgkmcnt(0)
	v_mfma_f32_16x16x32_bf16 v[144:147], v[120:123], v[210:213], v[144:147]
	v_mfma_f32_16x16x32_bf16 v[140:143], v[180:183], v[210:213], v[140:143]
	v_mfma_f32_16x16x32_bf16 v[112:115], v[120:123], v[218:221], v[112:115]
	v_mfma_f32_16x16x32_bf16 v[108:111], v[180:183], v[218:221], v[108:111]
	v_mfma_f32_16x16x32_bf16 v[96:99], v[120:123], v[226:229], v[96:99]
	v_mfma_f32_16x16x32_bf16 v[92:95], v[180:183], v[226:229], v[92:95]
	v_mfma_f32_16x16x32_bf16 v[80:83], v[120:123], v[234:237], v[80:83]
	v_mfma_f32_16x16x32_bf16 v[76:79], v[180:183], v[234:237], v[76:79]
	v_mfma_f32_16x16x32_bf16 v[144:147], v[176:179], v[214:217], v[144:147]
	v_mfma_f32_16x16x32_bf16 v[140:143], v[190:193], v[214:217], v[140:143]
	v_mfma_f32_16x16x32_bf16 v[112:115], v[176:179], v[222:225], v[112:115]
	v_mfma_f32_16x16x32_bf16 v[108:111], v[190:193], v[222:225], v[108:111]
	v_mfma_f32_16x16x32_bf16 v[96:99], v[176:179], v[230:233], v[96:99]
	v_mfma_f32_16x16x32_bf16 v[92:95], v[190:193], v[230:233], v[92:95]
	v_mfma_f32_16x16x32_bf16 v[80:83], v[176:179], v[238:241], v[80:83]
	v_mfma_f32_16x16x32_bf16 v[76:79], v[190:193], v[238:241], v[76:79]
	s_setprio 0
	s_setprio 1
	v_mfma_f32_16x16x32_bf16 v[124:127], v[194:197], v[210:213], v[124:127]
	v_mfma_f32_16x16x32_bf16 v[116:119], v[202:205], v[210:213], v[116:119]
	v_mfma_f32_16x16x32_bf16 v[104:107], v[194:197], v[218:221], v[104:107]
	v_mfma_f32_16x16x32_bf16 v[100:103], v[202:205], v[218:221], v[100:103]
	v_mfma_f32_16x16x32_bf16 v[88:91], v[194:197], v[226:229], v[88:91]
	v_mfma_f32_16x16x32_bf16 v[84:87], v[202:205], v[226:229], v[84:87]
	v_mfma_f32_16x16x32_bf16 v[72:75], v[194:197], v[234:237], v[72:75]
	v_mfma_f32_16x16x32_bf16 v[68:71], v[202:205], v[234:237], v[68:71]
	v_mfma_f32_16x16x32_bf16 v[124:127], v[198:201], v[214:217], v[124:127]
	v_mfma_f32_16x16x32_bf16 v[116:119], v[206:209], v[214:217], v[116:119]
	v_mfma_f32_16x16x32_bf16 v[104:107], v[198:201], v[222:225], v[104:107]
	v_mfma_f32_16x16x32_bf16 v[100:103], v[206:209], v[222:225], v[100:103]
	v_mfma_f32_16x16x32_bf16 v[88:91], v[198:201], v[230:233], v[88:91]
	v_mfma_f32_16x16x32_bf16 v[84:87], v[206:209], v[230:233], v[84:87]
	v_mfma_f32_16x16x32_bf16 v[72:75], v[198:201], v[238:241], v[72:75]
	v_mfma_f32_16x16x32_bf16 v[68:71], v[206:209], v[238:241], v[68:71]
	s_setprio 0
	s_barrier
	s_add_i32 s10, s14, s8
	v_lshl_add_u64 v[6:7], v[166:167], 0, s[18:19]
	s_mov_b32 m0, s10
	ds_read_b128 v[210:213], v173 offset:49152
	ds_read_b128 v[214:217], v173 offset:50176
	ds_read_b128 v[218:221], v173 offset:51200
	ds_read_b128 v[222:225], v173 offset:52224
	ds_read_b128 v[226:229], v173 offset:53248
	ds_read_b128 v[230:233], v173 offset:54272
	ds_read_b128 v[234:237], v173 offset:55296
	ds_read_b128 v[238:241], v173 offset:56320
	global_load_lds_dwordx4 v[6:7], off
	s_add_i32 m0, s10, 0x2000
	s_add_u32 s6, s6, 0x40080
	v_lshl_add_u64 v[6:7], v[184:185], 0, s[18:19]
	s_addc_u32 s7, s7, 0
	s_add_i32 s10, s15, s8
	global_load_lds_dwordx4 v[6:7], off
	v_lshl_add_u64 v[6:7], s[6:7], 0, v[150:151]
	s_mov_b32 m0, s10
	s_nop 0
	global_load_lds_dwordx4 v[6:7], off
	v_lshl_add_u64 v[6:7], s[6:7], 0, v[154:155]
	s_add_i32 m0, s10, 0x2000
	s_nop 0
	global_load_lds_dwordx4 v[6:7], off
	v_lshl_add_u64 v[6:7], v[186:187], 0, s[18:19]
	s_mov_b32 m0, s55
	s_nop 0
	global_load_lds_dwordx4 v[6:7], off
	v_lshl_add_u64 v[6:7], v[242:243], 0, s[18:19]
	s_mov_b32 m0, s58
	s_nop 0
	global_load_lds_dwordx4 v[6:7], off
	s_waitcnt vmcnt(8)
	s_waitcnt lgkmcnt(0)
	s_barrier
	s_setprio 1
	s_waitcnt lgkmcnt(0)
	v_mfma_f32_16x16x32_bf16 v[64:67], v[120:123], v[210:213], v[64:67]
	v_mfma_f32_16x16x32_bf16 v[60:63], v[180:183], v[210:213], v[60:63]
	v_mfma_f32_16x16x32_bf16 v[48:51], v[120:123], v[218:221], v[48:51]
	v_mfma_f32_16x16x32_bf16 v[44:47], v[180:183], v[218:221], v[44:47]
	v_mfma_f32_16x16x32_bf16 v[32:35], v[120:123], v[226:229], v[32:35]
	v_mfma_f32_16x16x32_bf16 v[28:31], v[180:183], v[226:229], v[28:31]
	v_mfma_f32_16x16x32_bf16 v[16:19], v[120:123], v[234:237], v[16:19]
	v_mfma_f32_16x16x32_bf16 v[12:15], v[180:183], v[234:237], v[12:15]
	v_mfma_f32_16x16x32_bf16 v[64:67], v[176:179], v[214:217], v[64:67]
	v_mfma_f32_16x16x32_bf16 v[60:63], v[190:193], v[214:217], v[60:63]
	v_mfma_f32_16x16x32_bf16 v[48:51], v[176:179], v[222:225], v[48:51]
	v_mfma_f32_16x16x32_bf16 v[44:47], v[190:193], v[222:225], v[44:47]
	v_mfma_f32_16x16x32_bf16 v[32:35], v[176:179], v[230:233], v[32:35]
	v_mfma_f32_16x16x32_bf16 v[28:31], v[190:193], v[230:233], v[28:31]
	v_mfma_f32_16x16x32_bf16 v[16:19], v[176:179], v[238:241], v[16:19]
	v_mfma_f32_16x16x32_bf16 v[12:15], v[190:193], v[238:241], v[12:15]
	s_setprio 0
	s_setprio 1
	v_mfma_f32_16x16x32_bf16 v[56:59], v[194:197], v[210:213], v[56:59]
	v_mfma_f32_16x16x32_bf16 v[52:55], v[202:205], v[210:213], v[52:55]
	v_mfma_f32_16x16x32_bf16 v[40:43], v[194:197], v[218:221], v[40:43]
	v_mfma_f32_16x16x32_bf16 v[36:39], v[202:205], v[218:221], v[36:39]
	v_mfma_f32_16x16x32_bf16 v[24:27], v[194:197], v[226:229], v[24:27]
	v_mfma_f32_16x16x32_bf16 v[20:23], v[202:205], v[226:229], v[20:23]
	v_mfma_f32_16x16x32_bf16 v[6:9], v[194:197], v[234:237], v[8:11]
	v_mfma_f32_16x16x32_bf16 v[2:5], v[202:205], v[234:237], v[2:5]
	v_mfma_f32_16x16x32_bf16 v[56:59], v[198:201], v[214:217], v[56:59]
	v_mfma_f32_16x16x32_bf16 v[52:55], v[206:209], v[214:217], v[52:55]
	v_mfma_f32_16x16x32_bf16 v[40:43], v[198:201], v[222:225], v[40:43]
	v_mfma_f32_16x16x32_bf16 v[36:39], v[206:209], v[222:225], v[36:39]
	v_mfma_f32_16x16x32_bf16 v[24:27], v[198:201], v[230:233], v[24:27]
	v_mfma_f32_16x16x32_bf16 v[20:23], v[206:209], v[230:233], v[20:23]
	v_mfma_f32_16x16x32_bf16 v[8:11], v[198:201], v[238:241], v[6:9]
	v_mfma_f32_16x16x32_bf16 v[4:7], v[206:209], v[238:241], v[2:5]
	s_setprio 0
	s_barrier
	s_add_i32 s76, s76, 2
	s_add_u32 s70, s70, 0x100
	s_addc_u32 s71, s71, 0
	s_cmp_gt_u32 s76, 13
	s_cbranch_scc1 .LBB0_901
